# wave-sum butterflies: xor-16/32 steps via v_permlane16/32_swap on two copies instead of ds_bpermute (conv LayerNorm, both norms)
# baseline (speedup 1.0000x reference)
; __device__ __forceinline__ int obid() { int b = (int)blockIdx.x; asm volatile("" : "+s"(b)); return b; }
; __device__ __forceinline__ void ph_norm(const Params& p_, int l, int skip_blocks) {
;     ...
;         for (int pi = (obid() - skip_blocks) * 8 + wave; pi >= 0 && pi < 4096; pi += nw) {
;             const int row = (pi >> 11) * 4096 + (pi & 2047);
;             const f32x4* xr0 = (const f32x4*)(xin + (size_t)row * DM) + lane; const f32x4* xr1 = (const f32x4*)(xin + (size_t)(row + stride) * DM) + lane;
;             const float* md = mod + (size_t)(l * 2 + (row >> 12)) * 6144;
;             f32x4 v0[8], v1[8], ca[8], cb[8];
; #pragma unroll
;             for (int j = 0; j < 8; ++j) { v0[j] = xr0[64 * j]; v1[j] = xr1[64 * j]; }
; #pragma unroll
;             for (int j = 0; j < 8; ++j) { const int col = (64 * j + lane) * 4; ca[j] = *(const f32x4*)(g + col) * (*(const f32x4*)(md + 2048 + col) + 1.f); cb[j] = *(const f32x4*)(md + col); }
.LBB0_204:
	v_and_b32_e32 v0, 0x7ff, v197
	v_and_or_b32 v200, v198, s74, v0
	v_lshlrev_b32_e32 v0, 13, v200
	v_lshl_or_b32 v199, v200, 11, v181
	v_lshl_add_u64 v[2:3], v[98:99], 0, v[0:1]
	v_lshlrev_b32_e32 v0, 2, v199
	v_lshl_add_u64 v[4:5], v[98:99], 0, v[0:1]
	v_lshrrev_b32_e32 v0, 11, v197
	v_or_b32_e32 v0, s3, v0
	v_mul_u32_u24_e32 v0, 0x1800, v0
	global_load_dwordx4 v[62:65], v[2:3], off
	global_load_dwordx4 v[58:61], v[4:5], off
	global_load_dwordx4 v[54:57], v[2:3], off offset:1024
	global_load_dwordx4 v[50:53], v[4:5], off offset:1024
	global_load_dwordx4 v[46:49], v[2:3], off offset:2048
	global_load_dwordx4 v[42:45], v[4:5], off offset:2048
	global_load_dwordx4 v[38:41], v[2:3], off offset:3072
	global_load_dwordx4 v[34:37], v[4:5], off offset:3072
	v_add_co_u32_e32 v2, vcc, s74, v2
	v_lshl_add_u64 v[94:95], v[0:1], 2, s[42:43]
	s_nop 0
	v_addc_co_u32_e32 v3, vcc, 0, v3, vcc
	v_add_co_u32_e32 v4, vcc, s74, v4
	v_lshl_add_u64 v[96:97], v[94:95], 0, s[26:27]
	v_mov_b32_e32 v113, v1
	v_addc_co_u32_e32 v5, vcc, 0, v5, vcc
	v_lshl_add_u64 v[70:71], v[96:97], 0, v[112:113]
	global_load_dwordx4 v[30:33], v[2:3], off
	global_load_dwordx4 v[26:29], v[4:5], off
	global_load_dwordx4 v[22:25], v[2:3], off offset:1024
	global_load_dwordx4 v[18:21], v[4:5], off offset:1024
	global_load_dwordx4 v[14:17], v[2:3], off offset:2048
	global_load_dwordx4 v[10:13], v[4:5], off offset:2048
	global_load_dwordx4 v[6:9], v[2:3], off offset:3072
	s_nop 0
	global_load_dwordx4 v[2:5], v[4:5], off offset:3072
	v_mov_b32_e32 v115, v1
	global_load_dwordx4 v[70:73], v[70:71], off
	v_lshl_add_u64 v[86:87], v[94:95], 0, v[112:113]
	global_load_dwordx4 v[66:69], v[100:101], off
	v_lshl_add_u64 v[74:75], v[96:97], 0, v[114:115]
	v_mov_b32_e32 v117, v1
	v_lshl_add_u64 v[78:79], v[96:97], 0, v[116:117]
	v_mov_b32_e32 v119, v1
	v_lshl_add_u64 v[82:83], v[96:97], 0, v[118:119]
	v_mov_b32_e32 v121, v1
	v_mov_b32_e32 v123, v1
	v_lshl_add_u64 v[90:91], v[96:97], 0, v[122:123]
	v_mov_b32_e32 v125, v1
	v_lshl_add_u64 v[166:167], v[96:97], 0, v[124:125]
	v_mov_b32_e32 v127, v1
	global_load_dwordx4 v[210:213], v[100:101], off offset:1024
	global_load_dwordx4 v[214:217], v[74:75], off
	global_load_dwordx4 v[218:221], v[100:101], off offset:2048
	global_load_dwordx4 v[222:225], v[78:79], off
	global_load_dwordx4 v[226:229], v[100:101], off offset:3072
	global_load_dwordx4 v[230:233], v[82:83], off
	global_load_dwordx4 v[234:237], v[102:103], off
	v_lshl_add_u64 v[250:251], v[96:97], 0, v[120:121]
	global_load_dwordx4 v[238:241], v[250:251], off
	global_load_dwordx4 v[242:245], v[104:105], off
	global_load_dwordx4 v[246:249], v[90:91], off
	v_xor_b32_e32 v119, 8, v178
	s_mov_b32 s12, 0x3a000000
	s_movk_i32 s9, 0xfff
	v_add_u32_e32 v198, s24, v198
	s_waitcnt vmcnt(10)
	v_mul_f32_e32 v0, v30, v30
	v_mul_f32_e32 v113, v31, v31
	v_mul_f32_e32 v115, v32, v32
	v_pk_add_f32 v[72:73], v[72:73], 1.0 op_sel_hi:[1,0]
	v_pk_add_f32 v[70:71], v[70:71], 1.0 op_sel_hi:[1,0]
	v_pk_mul_f32 v[128:129], v[68:69], v[72:73]
	v_pk_mul_f32 v[130:131], v[66:67], v[70:71]
	global_load_dwordx4 v[66:69], v[86:87], off
	v_mul_f32_e32 v117, v33, v33
	s_waitcnt vmcnt(9)
	v_pk_add_f32 v[216:217], v[216:217], 1.0 op_sel_hi:[1,0]
	v_pk_add_f32 v[214:215], v[214:215], 1.0 op_sel_hi:[1,0]
	v_pk_mul_f32 v[132:133], v[212:213], v[216:217]
	v_pk_mul_f32 v[134:135], v[210:211], v[214:215]
	global_load_dwordx4 v[70:73], v[86:87], off offset:1024
	s_nop 0
	s_waitcnt vmcnt(8)
	v_pk_add_f32 v[224:225], v[224:225], 1.0 op_sel_hi:[1,0]
	v_pk_add_f32 v[222:223], v[222:223], 1.0 op_sel_hi:[1,0]
	v_pk_mul_f32 v[136:137], v[220:221], v[224:225]
	v_pk_mul_f32 v[138:139], v[218:219], v[222:223]
	global_load_dwordx4 v[74:77], v[86:87], off offset:2048
	s_nop 0
	s_waitcnt vmcnt(7)
	v_pk_add_f32 v[232:233], v[232:233], 1.0 op_sel_hi:[1,0]
	v_pk_add_f32 v[230:231], v[230:231], 1.0 op_sel_hi:[1,0]
	v_pk_mul_f32 v[140:141], v[228:229], v[232:233]
	v_pk_mul_f32 v[142:143], v[226:227], v[230:231]
	global_load_dwordx4 v[78:81], v[86:87], off offset:3072
	v_lshl_add_u64 v[86:87], v[96:97], 0, v[120:121]
	v_lshl_add_u64 v[96:97], v[96:97], 0, v[126:127]
	s_waitcnt vmcnt(6)
	v_pk_add_f32 v[238:239], v[238:239], 1.0 op_sel_hi:[1,0]
	v_pk_add_f32 v[240:241], v[240:241], 1.0 op_sel_hi:[1,0]
	v_pk_mul_f32 v[160:161], v[234:235], v[238:239]
	v_lshl_add_u64 v[82:83], v[94:95], 0, v[120:121]
	v_pk_mul_f32 v[144:145], v[236:237], v[240:241]
	global_load_dwordx4 v[82:85], v[82:83], off
	s_nop 0
	v_xor_b32_e32 v121, 16, v178
	s_waitcnt vmcnt(5)
	v_pk_add_f32 v[246:247], v[246:247], 1.0 op_sel_hi:[1,0]
	v_pk_add_f32 v[248:249], v[248:249], 1.0 op_sel_hi:[1,0]
	v_pk_mul_f32 v[164:165], v[242:243], v[246:247]
	v_lshl_add_u64 v[86:87], v[94:95], 0, v[122:123]
	v_pk_mul_f32 v[162:163], v[244:245], v[248:249]
	global_load_dwordx4 v[86:89], v[86:87], off
	s_nop 0
	global_load_dwordx4 v[90:93], v[106:107], off
	v_xor_b32_e32 v123, 32, v178
	global_load_dwordx4 v[166:169], v[166:167], off
	s_waitcnt vmcnt(0)
	v_pk_add_f32 v[168:169], v[168:169], 1.0 op_sel_hi:[1,0]
	v_pk_add_f32 v[170:171], v[166:167], 1.0 op_sel_hi:[1,0]
	v_pk_mul_f32 v[166:167], v[92:93], v[168:169]
	v_pk_mul_f32 v[168:169], v[90:91], v[170:171]
	v_lshl_add_u64 v[90:91], v[94:95], 0, v[124:125]
	global_load_dwordx4 v[90:93], v[90:91], off
	s_nop 0
	global_load_dwordx4 v[172:175], v[108:109], off
	global_load_dwordx4 v[202:205], v[96:97], off
	v_lshl_add_u64 v[94:95], v[94:95], 0, v[126:127]
	s_waitcnt vmcnt(0)
; __device__ __forceinline__ void ph_norm(const Params& p_, int l, int skip_blocks) {
;     ...
;             float s0 = 0.f, s1 = 0.f;
; #pragma unroll
;             for (int j = 0; j < 8; ++j) { s0 += (v0[j][0] * v0[j][0] + v0[j][1] * v0[j][1]) + (v0[j][2] * v0[j][2] + v0[j][3] * v0[j][3]); s1 += (v1[j][0] * v1[j][0] + v1[j][1] * v1[j][1]) + (v1[j][2] * v1[j][2] + v1[j][3] * v1[j][3]); }
;             s0 = wave_sum(s0); s1 = wave_sum(s1);
	v_pk_add_f32 v[176:177], v[202:203], 1.0 op_sel_hi:[1,0]
	v_pk_add_f32 v[96:97], v[204:205], 1.0 op_sel_hi:[1,0]
	v_pk_mul_f32 v[172:173], v[172:173], v[176:177]
	v_mov_b32_e32 v176, v63
	v_mov_b32_e32 v177, v55
	v_pk_mul_f32 v[170:171], v[174:175], v[96:97]
	v_mov_b32_e32 v174, v62
	v_mov_b32_e32 v175, v54
	v_pk_mul_f32 v[176:177], v[176:177], v[176:177]
	v_mov_b32_e32 v202, v65
	v_mov_b32_e32 v203, v57
	v_pk_fma_f32 v[174:175], v[174:175], v[174:175], v[176:177]
	v_mov_b32_e32 v176, v64
	v_mov_b32_e32 v177, v56
	v_pk_mul_f32 v[202:203], v[202:203], v[202:203]
	v_mov_b32_e32 v204, v61
	v_pk_fma_f32 v[176:177], v[176:177], v[176:177], v[202:203]
	v_mov_b32_e32 v202, v59
	v_mov_b32_e32 v203, v51
	v_pk_add_f32 v[174:175], v[174:175], v[176:177]
	v_mov_b32_e32 v176, v58
	v_mov_b32_e32 v177, v50
	v_pk_mul_f32 v[202:203], v[202:203], v[202:203]
	v_mov_b32_e32 v205, v53
	v_pk_fma_f32 v[176:177], v[176:177], v[176:177], v[202:203]
	v_mov_b32_e32 v202, v60
	v_mov_b32_e32 v203, v52
	v_pk_mul_f32 v[204:205], v[204:205], v[204:205]
	v_pk_add_f32 v[174:175], v[174:175], v[174:175] op_sel:[0,1] op_sel_hi:[1,0]
	v_pk_fma_f32 v[202:203], v[202:203], v[202:203], v[204:205]
	v_pk_mul_f32 v[204:205], v[46:47], v[46:47]
	v_pk_add_f32 v[176:177], v[176:177], v[202:203]
	v_pk_mul_f32 v[202:203], v[48:49], v[48:49]
	v_mov_b32_e32 v175, v0
	v_pk_mov_b32 v[206:207], v[204:205], v[202:203] op_sel:[1,0]
	v_mov_b32_e32 v205, v203
	v_pk_add_f32 v[202:203], v[206:207], v[204:205]
	v_pk_mul_f32 v[204:205], v[44:45], v[44:45]
	v_pk_add_f32 v[202:203], v[202:203], v[202:203] op_sel:[0,1] op_sel_hi:[1,0]
	v_pk_mul_f32 v[206:207], v[42:43], v[42:43]
	v_mov_b32_e32 v203, v113
	v_mul_f32_e32 v0, v39, v39
	v_pk_mov_b32 v[208:209], v[206:207], v[204:205] op_sel:[1,0]
	v_mov_b32_e32 v207, v205
	v_pk_add_f32 v[174:175], v[174:175], v[202:203]
	v_pk_fma_f32 v[202:203], v[38:39], v[38:39], v[0:1] op_sel_hi:[1,1,0]
	v_mul_f32_e32 v0, v41, v41
	v_pk_add_f32 v[204:205], v[208:209], v[206:207]
	v_pk_fma_f32 v[206:207], v[40:41], v[40:41], v[0:1] op_sel_hi:[1,1,0]
	v_mov_b32_e32 v203, v115
	v_mov_b32_e32 v207, v117
	v_pk_add_f32 v[202:203], v[202:203], v[206:207]
	v_mul_f32_e32 v0, v26, v26
	v_pk_add_f32 v[174:175], v[174:175], v[202:203]
	v_mul_f32_e32 v113, v27, v27
	v_pk_add_f32 v[176:177], v[176:177], v[176:177] op_sel:[0,1] op_sel_hi:[1,0]
	v_pk_add_f32 v[202:203], v[204:205], v[204:205] op_sel:[0,1] op_sel_hi:[1,0]
	v_mov_b32_e32 v177, v0
	v_mov_b32_e32 v203, v113
	v_mul_f32_e32 v0, v35, v35
	v_pk_add_f32 v[176:177], v[176:177], v[202:203]
	v_pk_fma_f32 v[202:203], v[34:35], v[34:35], v[0:1] op_sel_hi:[1,1,0]
	v_mul_f32_e32 v0, v37, v37
	v_mul_f32_e32 v115, v28, v28
	v_mul_f32_e32 v117, v29, v29
	v_pk_fma_f32 v[204:205], v[36:37], v[36:37], v[0:1] op_sel_hi:[1,1,0]
	v_mov_b32_e32 v203, v115
	v_mov_b32_e32 v205, v117
	v_pk_add_f32 v[202:203], v[202:203], v[204:205]
	v_pk_mul_f32 v[204:205], v[22:23], v[22:23]
	v_pk_add_f32 v[176:177], v[176:177], v[202:203]
	v_pk_mul_f32 v[202:203], v[24:25], v[24:25]
	v_mul_f32_e32 v0, v6, v6
	v_pk_mov_b32 v[206:207], v[204:205], v[202:203] op_sel:[1,0]
	v_mov_b32_e32 v205, v203
	v_pk_add_f32 v[202:203], v[206:207], v[204:205]
	v_mul_f32_e32 v113, v7, v7
	v_pk_add_f32 v[174:175], v[174:175], v[174:175] op_sel:[0,1] op_sel_hi:[1,0]
	v_pk_add_f32 v[202:203], v[202:203], v[202:203] op_sel:[0,1] op_sel_hi:[1,0]
	v_pk_mul_f32 v[204:205], v[20:21], v[20:21]
	v_pk_mul_f32 v[206:207], v[18:19], v[18:19]
	v_mov_b32_e32 v175, v0
	v_mov_b32_e32 v203, v113
	v_mul_f32_e32 v0, v15, v15
	v_pk_mov_b32 v[208:209], v[206:207], v[204:205] op_sel:[1,0]
	v_mov_b32_e32 v207, v205
	v_pk_add_f32 v[174:175], v[174:175], v[202:203]
	v_pk_fma_f32 v[202:203], v[14:15], v[14:15], v[0:1] op_sel_hi:[1,1,0]
	v_mul_f32_e32 v0, v17, v17
	v_pk_add_f32 v[204:205], v[208:209], v[206:207]
	v_mul_f32_e32 v115, v8, v8
	v_mul_f32_e32 v117, v9, v9
	v_pk_fma_f32 v[206:207], v[16:17], v[16:17], v[0:1] op_sel_hi:[1,1,0]
	v_mov_b32_e32 v203, v115
	v_mov_b32_e32 v207, v117
	v_pk_add_f32 v[202:203], v[202:203], v[206:207]
	v_mul_f32_e32 v0, v2, v2
	v_pk_add_f32 v[174:175], v[174:175], v[202:203]
	v_mul_f32_e32 v113, v3, v3
	v_pk_add_f32 v[176:177], v[176:177], v[176:177] op_sel:[0,1] op_sel_hi:[1,0]
	v_pk_add_f32 v[202:203], v[204:205], v[204:205] op_sel:[0,1] op_sel_hi:[1,0]
	v_mov_b32_e32 v177, v0
	v_mov_b32_e32 v203, v113
	v_mul_f32_e32 v0, v11, v11
	v_pk_add_f32 v[176:177], v[176:177], v[202:203]
	v_pk_fma_f32 v[202:203], v[10:11], v[10:11], v[0:1] op_sel_hi:[1,1,0]
	v_mul_f32_e32 v0, v13, v13
	v_mul_f32_e32 v115, v4, v4
	v_mul_f32_e32 v117, v5, v5
	v_pk_fma_f32 v[204:205], v[12:13], v[12:13], v[0:1] op_sel_hi:[1,1,0]
	v_mov_b32_e32 v203, v115
	v_mov_b32_e32 v205, v117
	v_and_b32_e32 v0, 64, v178
	v_pk_add_f32 v[202:203], v[202:203], v[204:205]
	v_add_u32_e32 v0, 64, v0
	v_xor_b32_e32 v113, 1, v178
	v_pk_add_f32 v[176:177], v[176:177], v[202:203]
	v_cmp_lt_i32_e32 vcc, v113, v0
	v_mov_b32_e32 v202, v176
	v_mov_b32_e32 v203, v174
	v_cndmask_b32_e32 v113, v178, v113, vcc
	v_mov_b32_e32 v174, v177
	v_lshlrev_b32_e32 v113, 2, v113
	v_pk_add_f32 v[174:175], v[202:203], v[174:175]
	s_nop 1
	v_mov_b32_dpp v177, v175 quad_perm:[1,0,3,2] row_mask:0xf bank_mask:0xf
	v_mov_b32_dpp v176, v174 quad_perm:[1,0,3,2] row_mask:0xf bank_mask:0xf
	v_xor_b32_e32 v115, 2, v178
	v_cmp_lt_i32_e32 vcc, v115, v0
	v_xor_b32_e32 v117, 4, v178
	global_load_dwordx4 v[94:97], v[94:95], off
	v_cndmask_b32_e32 v115, v178, v115, vcc
	v_lshlrev_b32_e32 v115, 2, v115
	s_waitcnt lgkmcnt(0)
	v_pk_add_f32 v[174:175], v[174:175], v[176:177]
	s_nop 1
	v_mov_b32_dpp v177, v175 quad_perm:[2,3,0,1] row_mask:0xf bank_mask:0xf
	v_mov_b32_dpp v176, v174 quad_perm:[2,3,0,1] row_mask:0xf bank_mask:0xf
	v_cmp_lt_i32_e32 vcc, v117, v0
	s_waitcnt lgkmcnt(0)
; __device__ __forceinline__ unsigned pk2(float lo, float hi) { return f2bf(lo) | (f2bf(hi) << 16); }
; __device__ __forceinline__ void ph_norm(const Params& p_, int l, int skip_blocks) {
;     ...
;             s0 = wave_sum(s0); s1 = wave_sum(s1);
;             const float r0 = rsqrtf(s0 * (1.f / DM) + 1e-6f), r1 = rsqrtf(s1 * (1.f / DM) + 1e-6f);
; #pragma unroll
;             for (int j = 0; j < 8; ++j) { const int col = (64 * j + lane) * 4;
;                 const f32x4 o0 = (v0[j] * r0) * ca[j] + cb[j], o1 = (v1[j] * r1) * ca[j] + cb[j]; u32x2 w;
;                 w.x = pk2(o0[0], o0[1]); w.y = pk2(o0[2], o0[3]); *(u32x2*)(h + (size_t)row * DM + col) = w;
;                 w.x = pk2(o1[0], o1[1]); w.y = pk2(o1[2], o1[3]); *(u32x2*)(h + (size_t)(row + stride) * DM + col) = w; }
	v_pk_add_f32 v[174:175], v[174:175], v[176:177]
	v_cndmask_b32_e32 v117, v178, v117, vcc
	v_lshlrev_b32_e32 v117, 2, v117
	s_nop 1
	v_mov_b32_dpp v177, v175 row_half_mirror row_mask:0xf bank_mask:0xf
	v_mov_b32_dpp v176, v174 row_half_mirror row_mask:0xf bank_mask:0xf
	v_cmp_lt_i32_e32 vcc, v119, v0
	s_waitcnt lgkmcnt(0)
	v_pk_add_f32 v[174:175], v[174:175], v[176:177]
	v_cndmask_b32_e32 v119, v178, v119, vcc
	v_lshlrev_b32_e32 v119, 2, v119
	s_nop 1
	v_mov_b32_dpp v177, v175 row_mirror row_mask:0xf bank_mask:0xf
	v_mov_b32_dpp v176, v174 row_mirror row_mask:0xf bank_mask:0xf
	v_cmp_lt_i32_e32 vcc, v121, v0
	s_waitcnt lgkmcnt(0)
	v_pk_add_f32 v[174:175], v[174:175], v[176:177]
	v_cndmask_b32_e32 v121, v178, v121, vcc
	v_lshlrev_b32_e32 v121, 2, v121
	v_mov_b32_e32 v177, v175
	v_mov_b32_e32 v176, v174
	s_nop 1
	v_permlane16_swap_b32_e32 v175, v177
	v_permlane16_swap_b32_e32 v174, v176
	v_cmp_lt_i32_e32 vcc, v123, v0
	s_waitcnt lgkmcnt(0)
	v_pk_add_f32 v[174:175], v[174:175], v[176:177]
	v_cndmask_b32_e32 v0, v178, v123, vcc
	v_lshlrev_b32_e32 v0, 2, v0
	v_mov_b32_e32 v177, v175
	v_mov_b32_e32 v176, v174
	s_nop 1
	v_permlane32_swap_b32_e32 v175, v177
	v_permlane32_swap_b32_e32 v174, v176
	s_waitcnt lgkmcnt(0)
	v_pk_add_f32 v[174:175], v[174:175], v[176:177]
	s_nop 0
	v_pk_fma_f32 v[174:175], v[174:175], s[12:13], v[146:147] op_sel_hi:[1,0,0]
	s_nop 0
	v_mul_f32_e32 v0, 0x4b800000, v175
	v_cmp_gt_f32_e64 s[36:37], s92, v175
	v_cmp_gt_f32_e32 vcc, s92, v174
	s_nop 0
	v_cndmask_b32_e64 v0, v175, v0, s[36:37]
	v_rsq_f32_e32 v0, v0
	s_nop 0
	v_mul_f32_e32 v113, 0x45800000, v0
	v_cndmask_b32_e64 v176, v0, v113, s[36:37]
	v_mul_f32_e32 v0, 0x4b800000, v174
	v_cndmask_b32_e32 v0, v174, v0, vcc
	v_rsq_f32_e32 v0, v0
	v_pk_mul_f32 v[62:63], v[62:63], v[176:177] op_sel_hi:[1,0]
	v_pk_mul_f32 v[64:65], v[64:65], v[176:177] op_sel_hi:[1,0]
	v_pk_fma_f32 v[62:63], v[130:131], v[62:63], v[66:67]
	v_mul_f32_e32 v113, 0x45800000, v0
	v_cndmask_b32_e32 v174, v0, v113, vcc
	v_bfe_u32 v0, v62, 16, 1
	v_add3_u32 v0, v62, v0, s14
	v_bfe_u32 v62, v63, 16, 1
	v_pk_fma_f32 v[64:65], v[128:129], v[64:65], v[68:69]
	v_lshrrev_b32_e32 v0, 16, v0
	v_add3_u32 v62, v63, v62, s14
	v_and_or_b32 v62, v62, s15, v0
	v_bfe_u32 v0, v64, 16, 1
	v_add3_u32 v0, v64, v0, s14
	v_bfe_u32 v63, v65, 16, 1
	v_pk_mul_f32 v[58:59], v[58:59], v[174:175] op_sel_hi:[1,0]
	v_lshrrev_b32_e32 v0, 16, v0
	v_add3_u32 v63, v65, v63, s14
	v_pk_fma_f32 v[58:59], v[130:131], v[58:59], v[66:67]
	v_and_or_b32 v63, v63, s15, v0
	v_lshlrev_b32_e32 v0, 12, v200
	v_lshl_add_u64 v[64:65], v[110:111], 0, v[0:1]
	v_bfe_u32 v0, v58, 16, 1
	v_pk_mul_f32 v[60:61], v[60:61], v[174:175] op_sel_hi:[1,0]
	v_add3_u32 v0, v58, v0, s14
	v_bfe_u32 v58, v59, 16, 1
	v_pk_fma_f32 v[60:61], v[128:129], v[60:61], v[68:69]
	v_lshrrev_b32_e32 v0, 16, v0
	v_add3_u32 v58, v59, v58, s14
	v_and_or_b32 v58, v58, s15, v0
	v_bfe_u32 v0, v60, 16, 1
	v_add3_u32 v0, v60, v0, s14
	v_bfe_u32 v59, v61, 16, 1
	v_lshrrev_b32_e32 v0, 16, v0
	v_add3_u32 v59, v61, v59, s14
	v_pk_mul_f32 v[54:55], v[54:55], v[176:177] op_sel_hi:[1,0]
	v_and_or_b32 v59, v59, s15, v0
	v_lshlrev_b32_e32 v0, 1, v199
	v_pk_fma_f32 v[54:55], v[134:135], v[54:55], v[70:71]
	v_lshl_add_u64 v[60:61], v[110:111], 0, v[0:1]
	v_bfe_u32 v0, v54, 16, 1
	v_pk_mul_f32 v[56:57], v[56:57], v[176:177] op_sel_hi:[1,0]
	v_add3_u32 v0, v54, v0, s14
	v_bfe_u32 v54, v55, 16, 1
	v_pk_fma_f32 v[56:57], v[132:133], v[56:57], v[72:73]
	v_lshrrev_b32_e32 v0, 16, v0
	v_add3_u32 v54, v55, v54, s14
	v_and_or_b32 v54, v54, s15, v0
	v_bfe_u32 v0, v56, 16, 1
	v_pk_mul_f32 v[50:51], v[50:51], v[174:175] op_sel_hi:[1,0]
	v_add3_u32 v0, v56, v0, s14
	v_bfe_u32 v55, v57, 16, 1
	v_pk_fma_f32 v[50:51], v[134:135], v[50:51], v[70:71]
	v_lshrrev_b32_e32 v0, 16, v0
	v_add3_u32 v55, v57, v55, s14
	v_and_or_b32 v55, v55, s15, v0
	v_bfe_u32 v0, v50, 16, 1
	v_pk_mul_f32 v[52:53], v[52:53], v[174:175] op_sel_hi:[1,0]
	v_add3_u32 v0, v50, v0, s14
	v_bfe_u32 v50, v51, 16, 1
	v_pk_fma_f32 v[52:53], v[132:133], v[52:53], v[72:73]
	v_lshrrev_b32_e32 v0, 16, v0
	v_add3_u32 v50, v51, v50, s14
	v_and_or_b32 v50, v50, s15, v0
	v_bfe_u32 v0, v52, 16, 1
	v_add3_u32 v0, v52, v0, s14
	v_bfe_u32 v51, v53, 16, 1
	v_pk_mul_f32 v[46:47], v[46:47], v[176:177] op_sel_hi:[1,0]
	v_lshrrev_b32_e32 v0, 16, v0
	v_add3_u32 v51, v53, v51, s14
	v_pk_fma_f32 v[46:47], v[138:139], v[46:47], v[74:75]
	v_and_or_b32 v51, v51, s15, v0
	v_bfe_u32 v0, v46, 16, 1
	v_pk_mul_f32 v[48:49], v[48:49], v[176:177] op_sel_hi:[1,0]
	v_add3_u32 v0, v46, v0, s14
	v_bfe_u32 v46, v47, 16, 1
	v_pk_fma_f32 v[48:49], v[136:137], v[48:49], v[76:77]
	v_lshrrev_b32_e32 v0, 16, v0
	v_add3_u32 v46, v47, v46, s14
	v_and_or_b32 v46, v46, s15, v0
	v_bfe_u32 v0, v48, 16, 1
	v_pk_mul_f32 v[42:43], v[42:43], v[174:175] op_sel_hi:[1,0]
	v_add3_u32 v0, v48, v0, s14
	v_bfe_u32 v47, v49, 16, 1
	v_pk_fma_f32 v[42:43], v[138:139], v[42:43], v[74:75]
	v_lshrrev_b32_e32 v0, 16, v0
	v_add3_u32 v47, v49, v47, s14
	v_and_or_b32 v47, v47, s15, v0
	v_bfe_u32 v0, v42, 16, 1
	v_pk_mul_f32 v[44:45], v[44:45], v[174:175] op_sel_hi:[1,0]
	v_add3_u32 v0, v42, v0, s14
	v_bfe_u32 v42, v43, 16, 1
	v_pk_fma_f32 v[44:45], v[136:137], v[44:45], v[76:77]
	v_lshrrev_b32_e32 v0, 16, v0
	v_add3_u32 v42, v43, v42, s14
	v_and_or_b32 v42, v42, s15, v0
	v_bfe_u32 v0, v44, 16, 1
	v_add3_u32 v0, v44, v0, s14
	v_bfe_u32 v43, v45, 16, 1
	v_pk_mul_f32 v[38:39], v[38:39], v[176:177] op_sel_hi:[1,0]
	v_lshrrev_b32_e32 v0, 16, v0
	v_add3_u32 v43, v45, v43, s14
	v_pk_fma_f32 v[38:39], v[142:143], v[38:39], v[78:79]
	v_and_or_b32 v43, v43, s15, v0
	v_bfe_u32 v0, v38, 16, 1
	v_pk_mul_f32 v[40:41], v[40:41], v[176:177] op_sel_hi:[1,0]
; __device__ __forceinline__ unsigned pk2(float lo, float hi) { return f2bf(lo) | (f2bf(hi) << 16); }
; __device__ __forceinline__ void ph_norm(const Params& p_, int l, int skip_blocks) {
;     ...
;             for (int j = 0; j < 8; ++j) { const int col = (64 * j + lane) * 4;
;                 const f32x4 o0 = (v0[j] * r0) * ca[j] + cb[j], o1 = (v1[j] * r1) * ca[j] + cb[j]; u32x2 w;
;                 w.x = pk2(o0[0], o0[1]); w.y = pk2(o0[2], o0[3]); *(u32x2*)(h + (size_t)row * DM + col) = w;
;                 w.x = pk2(o1[0], o1[1]); w.y = pk2(o1[2], o1[3]); *(u32x2*)(h + (size_t)(row + stride) * DM + col) = w; }
	v_add3_u32 v0, v38, v0, s14
	v_bfe_u32 v38, v39, 16, 1
	v_pk_fma_f32 v[40:41], v[140:141], v[40:41], v[80:81]
	v_lshrrev_b32_e32 v0, 16, v0
	v_add3_u32 v38, v39, v38, s14
	v_and_or_b32 v38, v38, s15, v0
	v_bfe_u32 v0, v40, 16, 1
	v_pk_mul_f32 v[34:35], v[34:35], v[174:175] op_sel_hi:[1,0]
	v_add3_u32 v0, v40, v0, s14
	v_bfe_u32 v39, v41, 16, 1
	v_pk_fma_f32 v[34:35], v[142:143], v[34:35], v[78:79]
	v_lshrrev_b32_e32 v0, 16, v0
	v_add3_u32 v39, v41, v39, s14
	v_and_or_b32 v39, v39, s15, v0
	v_bfe_u32 v0, v34, 16, 1
	v_pk_mul_f32 v[36:37], v[36:37], v[174:175] op_sel_hi:[1,0]
	v_add3_u32 v0, v34, v0, s14
	v_bfe_u32 v34, v35, 16, 1
	v_pk_fma_f32 v[36:37], v[140:141], v[36:37], v[80:81]
	v_lshrrev_b32_e32 v0, 16, v0
	v_add3_u32 v34, v35, v34, s14
	v_and_or_b32 v34, v34, s15, v0
	v_bfe_u32 v0, v36, 16, 1
	v_add3_u32 v0, v36, v0, s14
	v_bfe_u32 v35, v37, 16, 1
	v_pk_mul_f32 v[30:31], v[30:31], v[176:177] op_sel_hi:[1,0]
	v_lshrrev_b32_e32 v0, 16, v0
	v_add3_u32 v35, v37, v35, s14
	v_pk_fma_f32 v[30:31], v[160:161], v[30:31], v[82:83]
	v_and_or_b32 v35, v35, s15, v0
	v_bfe_u32 v0, v30, 16, 1
	v_pk_mul_f32 v[32:33], v[32:33], v[176:177] op_sel_hi:[1,0]
	v_add3_u32 v0, v30, v0, s14
	v_bfe_u32 v30, v31, 16, 1
	v_pk_fma_f32 v[32:33], v[144:145], v[32:33], v[84:85]
	v_lshrrev_b32_e32 v0, 16, v0
	v_add3_u32 v30, v31, v30, s14
	v_and_or_b32 v30, v30, s15, v0
	v_bfe_u32 v0, v32, 16, 1
	v_pk_mul_f32 v[26:27], v[26:27], v[174:175] op_sel_hi:[1,0]
	v_add3_u32 v0, v32, v0, s14
	v_bfe_u32 v31, v33, 16, 1
	v_pk_fma_f32 v[26:27], v[160:161], v[26:27], v[82:83]
	v_lshrrev_b32_e32 v0, 16, v0
	v_add3_u32 v31, v33, v31, s14
	v_and_or_b32 v31, v31, s15, v0
	v_bfe_u32 v0, v26, 16, 1
	v_pk_mul_f32 v[28:29], v[28:29], v[174:175] op_sel_hi:[1,0]
	v_add3_u32 v0, v26, v0, s14
	v_bfe_u32 v26, v27, 16, 1
	v_pk_fma_f32 v[28:29], v[144:145], v[28:29], v[84:85]
	v_lshrrev_b32_e32 v0, 16, v0
	v_add3_u32 v26, v27, v26, s14
	v_and_or_b32 v26, v26, s15, v0
	v_bfe_u32 v0, v28, 16, 1
	v_add3_u32 v0, v28, v0, s14
	v_bfe_u32 v27, v29, 16, 1
	v_pk_mul_f32 v[22:23], v[22:23], v[176:177] op_sel_hi:[1,0]
	v_lshrrev_b32_e32 v0, 16, v0
	v_add3_u32 v27, v29, v27, s14
	v_pk_fma_f32 v[22:23], v[164:165], v[22:23], v[86:87]
	v_and_or_b32 v27, v27, s15, v0
	v_bfe_u32 v0, v22, 16, 1
	v_pk_mul_f32 v[24:25], v[24:25], v[176:177] op_sel_hi:[1,0]
	v_add3_u32 v0, v22, v0, s14
	v_bfe_u32 v22, v23, 16, 1
	v_pk_fma_f32 v[24:25], v[162:163], v[24:25], v[88:89]
	v_lshrrev_b32_e32 v0, 16, v0
	v_add3_u32 v22, v23, v22, s14
	v_and_or_b32 v22, v22, s15, v0
	v_bfe_u32 v0, v24, 16, 1
	v_pk_mul_f32 v[18:19], v[18:19], v[174:175] op_sel_hi:[1,0]
	v_add3_u32 v0, v24, v0, s14
	v_bfe_u32 v23, v25, 16, 1
	v_pk_fma_f32 v[18:19], v[164:165], v[18:19], v[86:87]
	v_lshrrev_b32_e32 v0, 16, v0
	v_add3_u32 v23, v25, v23, s14
	v_and_or_b32 v23, v23, s15, v0
	v_bfe_u32 v0, v18, 16, 1
	v_pk_mul_f32 v[20:21], v[20:21], v[174:175] op_sel_hi:[1,0]
	v_add3_u32 v0, v18, v0, s14
	v_bfe_u32 v18, v19, 16, 1
	v_pk_fma_f32 v[20:21], v[162:163], v[20:21], v[88:89]
	v_lshrrev_b32_e32 v0, 16, v0
	v_add3_u32 v18, v19, v18, s14
	v_and_or_b32 v18, v18, s15, v0
	v_bfe_u32 v0, v20, 16, 1
	v_add3_u32 v0, v20, v0, s14
	v_bfe_u32 v19, v21, 16, 1
	v_pk_mul_f32 v[14:15], v[14:15], v[176:177] op_sel_hi:[1,0]
	v_lshrrev_b32_e32 v0, 16, v0
	v_add3_u32 v19, v21, v19, s14
	v_pk_fma_f32 v[14:15], v[168:169], v[14:15], v[90:91]
	v_and_or_b32 v19, v19, s15, v0
	v_bfe_u32 v0, v14, 16, 1
	v_pk_mul_f32 v[16:17], v[16:17], v[176:177] op_sel_hi:[1,0]
	v_add3_u32 v0, v14, v0, s14
	v_bfe_u32 v14, v15, 16, 1
	v_pk_fma_f32 v[16:17], v[166:167], v[16:17], v[92:93]
	v_lshrrev_b32_e32 v0, 16, v0
	v_add3_u32 v14, v15, v14, s14
	v_and_or_b32 v14, v14, s15, v0
	v_bfe_u32 v0, v16, 16, 1
	v_pk_mul_f32 v[10:11], v[10:11], v[174:175] op_sel_hi:[1,0]
	v_add3_u32 v0, v16, v0, s14
	v_bfe_u32 v15, v17, 16, 1
	v_pk_fma_f32 v[10:11], v[168:169], v[10:11], v[90:91]
	v_lshrrev_b32_e32 v0, 16, v0
	v_add3_u32 v15, v17, v15, s14
	v_and_or_b32 v15, v15, s15, v0
	v_bfe_u32 v0, v10, 16, 1
	v_pk_mul_f32 v[12:13], v[12:13], v[174:175] op_sel_hi:[1,0]
	v_add3_u32 v0, v10, v0, s14
	v_bfe_u32 v10, v11, 16, 1
	v_pk_fma_f32 v[12:13], v[166:167], v[12:13], v[92:93]
	v_lshrrev_b32_e32 v0, 16, v0
	v_add3_u32 v10, v11, v10, s14
	v_and_or_b32 v10, v10, s15, v0
	v_bfe_u32 v0, v12, 16, 1
	v_add3_u32 v0, v12, v0, s14
	v_bfe_u32 v11, v13, 16, 1
	v_pk_mul_f32 v[6:7], v[6:7], v[176:177] op_sel_hi:[1,0]
	v_lshrrev_b32_e32 v0, 16, v0
	v_add3_u32 v11, v13, v11, s14
	s_waitcnt vmcnt(0)
	v_pk_fma_f32 v[6:7], v[172:173], v[6:7], v[94:95]
	v_and_or_b32 v11, v11, s15, v0
	v_bfe_u32 v0, v6, 16, 1
	v_pk_mul_f32 v[8:9], v[8:9], v[176:177] op_sel_hi:[1,0]
	v_add3_u32 v0, v6, v0, s14
	v_bfe_u32 v6, v7, 16, 1
	v_pk_fma_f32 v[8:9], v[170:171], v[8:9], v[96:97]
	v_lshrrev_b32_e32 v0, 16, v0
	v_add3_u32 v6, v7, v6, s14
	v_and_or_b32 v6, v6, s15, v0
	v_bfe_u32 v0, v8, 16, 1
	v_pk_mul_f32 v[2:3], v[2:3], v[174:175] op_sel_hi:[1,0]
	v_add3_u32 v0, v8, v0, s14
	v_bfe_u32 v7, v9, 16, 1
	v_pk_fma_f32 v[2:3], v[172:173], v[2:3], v[94:95]
	v_lshrrev_b32_e32 v0, 16, v0
	v_add3_u32 v7, v9, v7, s14
	v_and_or_b32 v7, v7, s15, v0
	v_bfe_u32 v0, v2, 16, 1
	v_pk_mul_f32 v[4:5], v[4:5], v[174:175] op_sel_hi:[1,0]
	v_add3_u32 v0, v2, v0, s14
	v_bfe_u32 v2, v3, 16, 1
	v_pk_fma_f32 v[4:5], v[170:171], v[4:5], v[96:97]
	v_lshrrev_b32_e32 v0, 16, v0
	v_add3_u32 v2, v3, v2, s14
	v_and_or_b32 v2, v2, s15, v0
	v_bfe_u32 v0, v4, 16, 1
	v_add3_u32 v0, v4, v0, s14
	v_bfe_u32 v3, v5, 16, 1
	v_lshrrev_b32_e32 v0, 16, v0
	v_add3_u32 v3, v5, v3, s14
	v_and_or_b32 v3, v3, s15, v0
	v_subrev_u32_e32 v0, s10, v197
	v_add_u32_e32 v197, 0x800, v0
	v_cmp_lt_u32_e32 vcc, s9, v197
	s_or_b64 s[46:47], vcc, s[46:47]
	global_store_dwordx2 v[64:65], v[62:63], off
	global_store_dwordx2 v[60:61], v[58:59], off
	global_store_dwordx2 v[64:65], v[54:55], off offset:512
	global_store_dwordx2 v[60:61], v[50:51], off offset:512
	global_store_dwordx2 v[64:65], v[46:47], off offset:1024
	global_store_dwordx2 v[60:61], v[42:43], off offset:1024
	global_store_dwordx2 v[64:65], v[38:39], off offset:1536
	global_store_dwordx2 v[60:61], v[34:35], off offset:1536
	global_store_dwordx2 v[64:65], v[30:31], off offset:2048
	global_store_dwordx2 v[60:61], v[26:27], off offset:2048
	global_store_dwordx2 v[64:65], v[22:23], off offset:2560
	global_store_dwordx2 v[60:61], v[18:19], off offset:2560
	global_store_dwordx2 v[64:65], v[14:15], off offset:3072
	global_store_dwordx2 v[60:61], v[10:11], off offset:3072
	global_store_dwordx2 v[64:65], v[6:7], off offset:3584
	global_store_dwordx2 v[60:61], v[2:3], off offset:3584
	s_andn2_b64 exec, exec, s[46:47]
	s_cbranch_execnz .LBB0_204

; __device__ __forceinline__ void conv_task(const Params& p_, int l, int task, unsigned char* lds) {
;     ...
;     float w[31];
; #pragma unroll
;     for (int k = 0; k < 31; ++k) w[k] = p.conv_w[(size_t)(l * 31 + k) * DG + tid];
;     const float cb = p.conv_b[l * DG + tid];
;     __syncthreads();
;     { float y[16];
; #pragma unroll
;       for (int t = 0; t < 16; ++t) y[t] = cb;
; #pragma unroll
;       for (int j = 0; j < 46; ++j) { const float u = us[j * 512 + tid];
.LBB0_426:
	s_or_b64 exec, exec, s[38:39]
	s_waitcnt vmcnt(0) lgkmcnt(0)
	v_mov_b32_e32 v2, s56
	v_mov_b32_e32 v3, s57
	v_ashrrev_i32_e32 v55, 31, v54
	v_lshl_add_u64 v[2:3], v[54:55], 2, v[2:3]
	v_lshl_add_u64 v[2:3], s[24:25], 2, v[2:3]
	v_add_co_u32_e32 v6, vcc, s74, v2
	s_movk_i32 s6, 0x5000
	s_nop 0
	v_addc_co_u32_e32 v7, vcc, 0, v3, vcc
	v_add_co_u32_e32 v8, vcc, s97, v2
	global_load_dword v33, v[2:3], off
	global_load_dword v0, v[2:3], off offset:2048
	global_load_dword v32, v[6:7], off offset:2048
	v_addc_co_u32_e32 v9, vcc, 0, v3, vcc
	v_add_co_u32_e32 v6, vcc, s5, v2
	v_add_u32_e32 v24, s3, v54
	s_nop 0
	v_addc_co_u32_e32 v7, vcc, 0, v3, vcc
	v_add_co_u32_e32 v10, vcc, s7, v2
	v_mov_b32_e32 v4, s58
	s_nop 0
	v_addc_co_u32_e32 v11, vcc, 0, v3, vcc
	v_add_co_u32_e32 v12, vcc, s6, v2
	s_movk_i32 s6, 0x7000
	s_nop 0
	v_addc_co_u32_e32 v13, vcc, 0, v3, vcc
	v_add_co_u32_e32 v14, vcc, s93, v2
	v_mov_b32_e32 v5, s59
	s_nop 0
	v_addc_co_u32_e32 v15, vcc, 0, v3, vcc
	global_load_dword v41, v[8:9], off offset:-4096
	global_load_dword v40, v[8:9], off
	global_load_dword v39, v[8:9], off offset:2048
	global_load_dword v38, v[10:11], off offset:-4096
	global_load_dword v36, v[10:11], off
	global_load_dword v35, v[10:11], off offset:2048
	global_load_dword v37, v[14:15], off offset:-4096
	global_load_dword v34, v[14:15], off
	v_add_co_u32_e32 v8, vcc, s6, v2
	s_mov_b32 s6, 0x8000
	s_nop 0
	v_addc_co_u32_e32 v9, vcc, 0, v3, vcc
	v_add_co_u32_e32 v10, vcc, s6, v2
	s_mov_b32 s6, 0x9000
	s_nop 0
	v_addc_co_u32_e32 v11, vcc, 0, v3, vcc
	v_add_co_u32_e32 v16, vcc, s6, v2
	s_mov_b32 s6, 0xb000
	s_nop 0
	v_addc_co_u32_e32 v17, vcc, 0, v3, vcc
	v_add_co_u32_e32 v18, vcc, s96, v2
	v_ashrrev_i32_e32 v25, 31, v24
	s_nop 0
	v_addc_co_u32_e32 v19, vcc, 0, v3, vcc
	v_add_co_u32_e32 v20, vcc, s6, v2
	s_mov_b32 s6, 0xc000
	s_nop 0
	v_addc_co_u32_e32 v21, vcc, 0, v3, vcc
	v_add_co_u32_e32 v22, vcc, s6, v2
	v_lshl_add_u64 v[4:5], v[24:25], 2, v[4:5]
	s_nop 0
	v_addc_co_u32_e32 v23, vcc, 0, v3, vcc
	global_load_dword v42, v[4:5], off
	global_load_dword v61, v[14:15], off offset:2048
	global_load_dword v57, v[10:11], off offset:-4096
	global_load_dword v52, v[10:11], off
	global_load_dword v50, v[10:11], off offset:2048
	global_load_dword v48, v[18:19], off offset:-4096
	global_load_dword v45, v[18:19], off
	global_load_dword v44, v[18:19], off offset:2048
	global_load_dword v43, v[22:23], off offset:-4096
	global_load_dword v65, v[6:7], off offset:2048
	global_load_dword v64, v[12:13], off offset:2048
	global_load_dword v63, v[8:9], off offset:2048
	global_load_dword v58, v[16:17], off offset:2048
	global_load_dword v46, v[20:21], off offset:2048
	s_mov_b32 s6, 0xd000
	v_add_co_u32_e32 v4, vcc, s6, v2
	s_mov_b32 s6, 0xe000
	s_nop 0
	v_addc_co_u32_e32 v5, vcc, 0, v3, vcc
	v_add_co_u32_e32 v6, vcc, s6, v2
	s_mov_b32 s6, 0xf000
	s_nop 0
	v_addc_co_u32_e32 v7, vcc, 0, v3, vcc
	global_load_dword v47, v[4:5], off offset:2048
	global_load_dword v62, v[22:23], off
	global_load_dword v59, v[22:23], off offset:2048
	global_load_dword v53, v[6:7], off offset:-4096
	global_load_dword v51, v[6:7], off
	global_load_dword v49, v[6:7], off offset:2048
	v_add_co_u32_e32 v2, vcc, s6, v2
	v_lshlrev_b32_e32 v60, 2, v54
	s_nop 0
	v_addc_co_u32_e32 v3, vcc, 0, v3, vcc
	global_load_dword v55, v[2:3], off
	v_add_u32_e32 v66, 0, v60
	s_barrier
	ds_read2st64_b32 v[80:81], v66 offset1:8
	ds_read2st64_b32 v[30:31], v66 offset0:16 offset1:24
	ds_read2st64_b32 v[28:29], v66 offset0:32 offset1:40
	ds_read2st64_b32 v[26:27], v66 offset0:48 offset1:56
	ds_read2st64_b32 v[24:25], v66 offset0:64 offset1:72
	ds_read2st64_b32 v[22:23], v66 offset0:80 offset1:88
	ds_read2st64_b32 v[20:21], v66 offset0:96 offset1:104
	ds_read2st64_b32 v[18:19], v66 offset0:112 offset1:120
	ds_read2st64_b32 v[16:17], v66 offset0:128 offset1:136
	ds_read2st64_b32 v[14:15], v66 offset0:144 offset1:152
	ds_read2st64_b32 v[12:13], v66 offset0:160 offset1:168
	ds_read2st64_b32 v[10:11], v66 offset0:176 offset1:184
	ds_read2st64_b32 v[8:9], v66 offset0:192 offset1:200
	ds_read2st64_b32 v[6:7], v66 offset0:208 offset1:216
	ds_read2st64_b32 v[4:5], v66 offset0:224 offset1:232
	ds_read2st64_b32 v[2:3], v66 offset0:240 offset1:248
	v_add_u32_e32 v67, 0x10000, v66
	v_add_u32_e32 v68, 0x10800, v66
	v_add_u32_e32 v69, 0x11000, v66
	v_add_u32_e32 v70, 0x11800, v66
	v_add_u32_e32 v74, 0x12000, v66
	v_add_u32_e32 v76, 0x12800, v66
	v_add_u32_e32 v77, 0x13000, v66
	v_add_u32_e32 v78, 0x13800, v66
	ds_read_b32 v75, v67
	ds_read_b32 v73, v68
	ds_read_b32 v72, v69
	ds_read_b32 v71, v70
	ds_read_b32 v70, v74
	ds_read_b32 v69, v76
	ds_read_b32 v68, v77
	ds_read_b32 v67, v78
	v_add_u32_e32 v74, 0x14000, v66
	v_add_u32_e32 v76, 0x14800, v66
	v_add_u32_e32 v77, 0x15000, v66
	v_add_u32_e32 v82, 0x15800, v66
	v_add_u32_e32 v83, 0x16000, v66
	v_add_u32_e32 v66, 0x16800, v66
	ds_read_b32 v79, v74
	ds_read_b32 v78, v76
	ds_read_b32 v77, v77
	ds_read_b32 v76, v82
	ds_read_b32 v74, v83
	ds_read_b32 v82, v66
	v_readlane_b32 s6, v255, 25
	s_add_i32 s26, s26, -1
	s_cmp_eq_u32 s26, 0
	s_cselect_b64 s[38:39], -1, 0
	s_add_u32 s40, s50, 0x12520000
	s_addc_u32 s41, s51, 0
	s_add_i32 s27, s27, 0x100
	s_max_u32 s27, s27, 0x200
	s_mov_b32 s9, s27
	s_mov_b64 s[48:49], 0
	s_waitcnt vmcnt(20) lgkmcnt(14)
; __device__ __forceinline__ void conv_task(const Params& p_, int l, int task, unsigned char* lds) {
;     ...
;     { float y[16];
; #pragma unroll
;       for (int t = 0; t < 16; ++t) y[t] = cb;
; #pragma unroll
;       for (int j = 0; j < 46; ++j) { const float u = us[j * 512 + tid];
; #pragma unroll
;           for (int t = 0; t < 16; ++t) { const int k = j - t; if (k >= 0 && k < 31) y[t] += w[k] * u; } }
	v_fma_f32 v80, v33, v80, v42
	v_fmac_f32_e32 v80, v0, v81
	v_fma_f32 v81, v33, v81, v42
	v_fmac_f32_e32 v80, v41, v30
	v_fmac_f32_e32 v81, v0, v30
	v_fma_f32 v30, v33, v30, v42
	v_fmac_f32_e32 v80, v32, v31
	v_fmac_f32_e32 v81, v41, v31
	v_fmac_f32_e32 v30, v0, v31
	v_fma_f32 v31, v33, v31, v42
	v_fmac_f32_e32 v80, v40, v28
	v_fmac_f32_e32 v81, v32, v28
	v_fmac_f32_e32 v30, v41, v28
	v_fmac_f32_e32 v31, v0, v28
	v_fma_f32 v28, v33, v28, v42
	v_fmac_f32_e32 v80, v39, v29
	v_fmac_f32_e32 v81, v40, v29
	v_fmac_f32_e32 v30, v32, v29
	v_fmac_f32_e32 v31, v41, v29
	v_fmac_f32_e32 v28, v0, v29
	v_fma_f32 v29, v33, v29, v42
	v_fmac_f32_e32 v80, v38, v26
	v_fmac_f32_e32 v81, v39, v26
	v_fmac_f32_e32 v30, v40, v26
	v_fmac_f32_e32 v31, v32, v26
	v_fmac_f32_e32 v28, v41, v26
	v_fmac_f32_e32 v29, v0, v26
	v_fma_f32 v26, v33, v26, v42
	s_waitcnt vmcnt(11)
	v_fmac_f32_e32 v80, v65, v27
	v_fmac_f32_e32 v81, v38, v27
	v_fmac_f32_e32 v30, v39, v27
	v_fmac_f32_e32 v31, v40, v27
	v_fmac_f32_e32 v28, v32, v27
	v_fmac_f32_e32 v29, v41, v27
	v_fmac_f32_e32 v26, v0, v27
	v_fma_f32 v27, v33, v27, v42
	v_fmac_f32_e32 v80, v36, v24
	v_fmac_f32_e32 v81, v65, v24
	v_fmac_f32_e32 v30, v38, v24
	v_fmac_f32_e32 v31, v39, v24
	v_fmac_f32_e32 v28, v40, v24
	v_fmac_f32_e32 v29, v32, v24
	v_fmac_f32_e32 v26, v41, v24
	v_fmac_f32_e32 v27, v0, v24
	v_fma_f32 v24, v33, v24, v42
	v_fmac_f32_e32 v80, v35, v25
	v_fmac_f32_e32 v81, v36, v25
	v_fmac_f32_e32 v30, v65, v25
	v_fmac_f32_e32 v31, v38, v25
	v_fmac_f32_e32 v28, v39, v25
	v_fmac_f32_e32 v29, v40, v25
	v_fmac_f32_e32 v26, v32, v25
	v_fmac_f32_e32 v27, v41, v25
	v_fmac_f32_e32 v24, v0, v25
	v_fma_f32 v25, v33, v25, v42
	v_fmac_f32_e32 v80, v37, v22
	v_fmac_f32_e32 v81, v35, v22
	v_fmac_f32_e32 v30, v36, v22
	v_fmac_f32_e32 v31, v65, v22
	v_fmac_f32_e32 v28, v38, v22
	v_fmac_f32_e32 v29, v39, v22
	v_fmac_f32_e32 v26, v40, v22
	v_fmac_f32_e32 v27, v32, v22
	v_fmac_f32_e32 v24, v41, v22
	v_fmac_f32_e32 v25, v0, v22
	v_fma_f32 v22, v33, v22, v42
	s_waitcnt vmcnt(10)
	v_fmac_f32_e32 v80, v64, v23
	v_fmac_f32_e32 v81, v37, v23
	v_fmac_f32_e32 v30, v35, v23
	v_fmac_f32_e32 v31, v36, v23
	v_fmac_f32_e32 v28, v65, v23
	v_fmac_f32_e32 v29, v38, v23
	v_fmac_f32_e32 v26, v39, v23
	v_fmac_f32_e32 v27, v40, v23
	v_fmac_f32_e32 v24, v32, v23
	v_fmac_f32_e32 v25, v41, v23
	v_fmac_f32_e32 v22, v0, v23
	v_fma_f32 v23, v33, v23, v42
	v_fmac_f32_e32 v80, v34, v20
	v_fmac_f32_e32 v81, v64, v20
	v_fmac_f32_e32 v30, v37, v20
	v_fmac_f32_e32 v31, v35, v20
	v_fmac_f32_e32 v28, v36, v20
	v_fmac_f32_e32 v29, v65, v20
	v_fmac_f32_e32 v26, v38, v20
	v_fmac_f32_e32 v27, v39, v20
	v_fmac_f32_e32 v24, v40, v20
	v_fmac_f32_e32 v25, v32, v20
	v_fmac_f32_e32 v22, v41, v20
	v_fmac_f32_e32 v23, v0, v20
	v_fma_f32 v20, v33, v20, v42
	v_fma_f32 v66, v33, v19, v42
	v_fmac_f32_e32 v80, v61, v21
	v_fmac_f32_e32 v81, v34, v21
	v_fmac_f32_e32 v30, v64, v21
	v_fmac_f32_e32 v31, v37, v21
	v_fmac_f32_e32 v28, v35, v21
	v_fmac_f32_e32 v29, v36, v21
	v_fmac_f32_e32 v26, v65, v21
	v_fmac_f32_e32 v27, v38, v21
	v_fmac_f32_e32 v24, v39, v21
	v_fmac_f32_e32 v25, v40, v21
	v_fmac_f32_e32 v22, v32, v21
	v_fmac_f32_e32 v23, v41, v21
	v_fmac_f32_e32 v20, v0, v21
	v_fma_f32 v21, v33, v21, v42
	v_fmac_f32_e32 v42, v33, v18
	v_fmac_f32_e32 v66, v0, v16
	v_fmac_f32_e32 v21, v0, v18
	v_fmac_f32_e32 v42, v0, v19
	v_fmac_f32_e32 v66, v41, v17
	v_fmac_f32_e32 v20, v41, v18
	v_fmac_f32_e32 v21, v41, v19
	v_fmac_f32_e32 v42, v41, v16
	v_fmac_f32_e32 v66, v32, v14
	v_fmac_f32_e32 v80, v57, v18
	v_fmac_f32_e32 v81, v61, v18
	v_fmac_f32_e32 v30, v34, v18
	v_fmac_f32_e32 v31, v64, v18
	v_fmac_f32_e32 v28, v37, v18
	v_fmac_f32_e32 v29, v35, v18
	v_fmac_f32_e32 v26, v36, v18
	v_fmac_f32_e32 v27, v65, v18
	v_fmac_f32_e32 v24, v38, v18
	v_fmac_f32_e32 v25, v39, v18
	v_fmac_f32_e32 v22, v40, v18
	v_fmac_f32_e32 v23, v32, v18
	v_fmac_f32_e32 v20, v32, v19
	v_fmac_f32_e32 v21, v32, v16
	v_fmac_f32_e32 v42, v32, v17
	v_fmac_f32_e32 v66, v40, v15
	s_waitcnt vmcnt(9)
	v_fmac_f32_e32 v80, v63, v19
	v_fmac_f32_e32 v81, v57, v19
	v_fmac_f32_e32 v30, v61, v19
	v_fmac_f32_e32 v31, v34, v19
	v_fmac_f32_e32 v28, v64, v19
	v_fmac_f32_e32 v29, v37, v19
	v_fmac_f32_e32 v26, v35, v19
	v_fmac_f32_e32 v27, v36, v19
	v_fmac_f32_e32 v24, v65, v19
	v_fmac_f32_e32 v25, v38, v19
	v_fmac_f32_e32 v22, v39, v19
	v_fmac_f32_e32 v23, v40, v19
	v_fmac_f32_e32 v20, v40, v16
	v_fmac_f32_e32 v21, v40, v17
	v_fmac_f32_e32 v42, v40, v14
	v_fmac_f32_e32 v66, v39, v12
	v_fmac_f32_e32 v80, v52, v16
	v_fmac_f32_e32 v81, v63, v16
	v_fmac_f32_e32 v30, v57, v16
	v_fmac_f32_e32 v31, v61, v16
	v_fmac_f32_e32 v28, v34, v16
	v_fmac_f32_e32 v29, v64, v16
	v_fmac_f32_e32 v26, v37, v16
	v_fmac_f32_e32 v27, v35, v16
	v_fmac_f32_e32 v24, v36, v16
	v_fmac_f32_e32 v25, v65, v16
	v_fmac_f32_e32 v22, v38, v16
	v_fmac_f32_e32 v23, v39, v16
	v_fmac_f32_e32 v20, v39, v17
	v_fmac_f32_e32 v21, v39, v14
	v_fmac_f32_e32 v42, v39, v15
	v_fmac_f32_e32 v66, v38, v13
	v_fmac_f32_e32 v80, v50, v17
	v_fmac_f32_e32 v81, v52, v17
	v_fmac_f32_e32 v30, v63, v17
	v_fmac_f32_e32 v31, v57, v17
	v_fmac_f32_e32 v28, v61, v17
	v_fmac_f32_e32 v29, v34, v17
	v_fmac_f32_e32 v26, v64, v17
	v_fmac_f32_e32 v27, v37, v17
	v_fmac_f32_e32 v24, v35, v17
	v_fmac_f32_e32 v25, v36, v17
	v_fmac_f32_e32 v22, v65, v17
	v_fmac_f32_e32 v23, v38, v17
	v_fmac_f32_e32 v20, v38, v14
	v_fmac_f32_e32 v21, v38, v15
	v_fmac_f32_e32 v42, v38, v12
	v_fmac_f32_e32 v66, v65, v10
	v_fmac_f32_e32 v80, v48, v14
	v_fmac_f32_e32 v81, v50, v14
	v_fmac_f32_e32 v30, v52, v14
	v_fmac_f32_e32 v31, v63, v14
	v_fmac_f32_e32 v28, v57, v14
	v_fmac_f32_e32 v29, v61, v14
	v_fmac_f32_e32 v26, v34, v14
	v_fmac_f32_e32 v27, v64, v14
	v_fmac_f32_e32 v24, v37, v14
	v_fmac_f32_e32 v25, v35, v14
	v_fmac_f32_e32 v22, v36, v14
	v_fmac_f32_e32 v23, v65, v14
	v_fmac_f32_e32 v20, v65, v15
	v_fmac_f32_e32 v21, v65, v12
	v_fmac_f32_e32 v42, v65, v13
	v_fmac_f32_e32 v66, v36, v11
	s_waitcnt vmcnt(8)
; __device__ __forceinline__ void conv_task(const Params& p_, int l, int task, unsigned char* lds) {
;     ...
;       for (int j = 0; j < 46; ++j) { const float u = us[j * 512 + tid];
; #pragma unroll
;           for (int t = 0; t < 16; ++t) { const int k = j - t; if (k >= 0 && k < 31) y[t] += w[k] * u; } }
	v_fmac_f32_e32 v80, v58, v15
	v_fmac_f32_e32 v81, v48, v15
	v_fmac_f32_e32 v30, v50, v15
	v_fmac_f32_e32 v31, v52, v15
	v_fmac_f32_e32 v28, v63, v15
	v_fmac_f32_e32 v29, v57, v15
	v_fmac_f32_e32 v26, v61, v15
	v_fmac_f32_e32 v27, v34, v15
	v_fmac_f32_e32 v24, v64, v15
	v_fmac_f32_e32 v25, v37, v15
	v_fmac_f32_e32 v22, v35, v15
	v_fmac_f32_e32 v23, v36, v15
	v_fmac_f32_e32 v20, v36, v12
	v_fmac_f32_e32 v21, v36, v13
	v_fmac_f32_e32 v42, v36, v10
	v_fmac_f32_e32 v66, v35, v8
	v_fmac_f32_e32 v80, v45, v12
	v_fmac_f32_e32 v81, v58, v12
	v_fmac_f32_e32 v30, v48, v12
	v_fmac_f32_e32 v31, v50, v12
	v_fmac_f32_e32 v28, v52, v12
	v_fmac_f32_e32 v29, v63, v12
	v_fmac_f32_e32 v26, v57, v12
	v_fmac_f32_e32 v27, v61, v12
	v_fmac_f32_e32 v24, v34, v12
	v_fmac_f32_e32 v25, v64, v12
	v_fmac_f32_e32 v22, v37, v12
	v_fmac_f32_e32 v23, v35, v12
	v_fmac_f32_e32 v20, v35, v13
	v_fmac_f32_e32 v21, v35, v10
	v_fmac_f32_e32 v42, v35, v11
	v_fmac_f32_e32 v66, v37, v9
	v_fmac_f32_e32 v80, v44, v13
	v_fmac_f32_e32 v81, v45, v13
	v_fmac_f32_e32 v30, v58, v13
	v_fmac_f32_e32 v31, v48, v13
	v_fmac_f32_e32 v28, v50, v13
	v_fmac_f32_e32 v29, v52, v13
	v_fmac_f32_e32 v26, v63, v13
	v_fmac_f32_e32 v27, v57, v13
	v_fmac_f32_e32 v24, v61, v13
	v_fmac_f32_e32 v25, v34, v13
	v_fmac_f32_e32 v22, v64, v13
	v_fmac_f32_e32 v23, v37, v13
	v_fmac_f32_e32 v20, v37, v10
	v_fmac_f32_e32 v21, v37, v11
	v_fmac_f32_e32 v42, v37, v8
	v_fmac_f32_e32 v66, v64, v6
	v_fmac_f32_e32 v80, v43, v10
	v_fmac_f32_e32 v81, v44, v10
	v_fmac_f32_e32 v30, v45, v10
	v_fmac_f32_e32 v31, v58, v10
	v_fmac_f32_e32 v28, v48, v10
	v_fmac_f32_e32 v29, v50, v10
	v_fmac_f32_e32 v26, v52, v10
	v_fmac_f32_e32 v27, v63, v10
	v_fmac_f32_e32 v24, v57, v10
	v_fmac_f32_e32 v25, v61, v10
	v_fmac_f32_e32 v22, v34, v10
	v_fmac_f32_e32 v23, v64, v10
	v_fmac_f32_e32 v20, v64, v11
	v_fmac_f32_e32 v21, v64, v8
	v_fmac_f32_e32 v42, v64, v9
	v_fmac_f32_e32 v66, v34, v7
	s_waitcnt vmcnt(7)
	v_fmac_f32_e32 v80, v46, v11
	v_fmac_f32_e32 v81, v43, v11
	v_fmac_f32_e32 v30, v44, v11
	v_fmac_f32_e32 v31, v45, v11
	v_fmac_f32_e32 v28, v58, v11
	v_fmac_f32_e32 v29, v48, v11
	v_fmac_f32_e32 v26, v50, v11
	v_fmac_f32_e32 v27, v52, v11
	v_fmac_f32_e32 v24, v63, v11
	v_fmac_f32_e32 v25, v57, v11
	v_fmac_f32_e32 v22, v61, v11
	v_fmac_f32_e32 v23, v34, v11
	v_fmac_f32_e32 v20, v34, v8
	v_fmac_f32_e32 v21, v34, v9
	v_fmac_f32_e32 v42, v34, v6
	v_fmac_f32_e32 v66, v61, v4
	s_waitcnt vmcnt(5)
	v_fmac_f32_e32 v80, v62, v8
	v_fmac_f32_e32 v81, v46, v8
	v_fmac_f32_e32 v30, v43, v8
	v_fmac_f32_e32 v31, v44, v8
	v_fmac_f32_e32 v28, v45, v8
	v_fmac_f32_e32 v29, v58, v8
	v_fmac_f32_e32 v26, v48, v8
	v_fmac_f32_e32 v27, v50, v8
	v_fmac_f32_e32 v24, v52, v8
	v_fmac_f32_e32 v25, v63, v8
	v_fmac_f32_e32 v22, v57, v8
	v_fmac_f32_e32 v23, v61, v8
	v_fmac_f32_e32 v20, v61, v9
	v_fmac_f32_e32 v21, v61, v6
	v_fmac_f32_e32 v42, v61, v7
	v_fmac_f32_e32 v66, v57, v5
	s_waitcnt vmcnt(4)
	v_fmac_f32_e32 v80, v59, v9
	v_fmac_f32_e32 v81, v62, v9
	v_fmac_f32_e32 v30, v46, v9
	v_fmac_f32_e32 v31, v43, v9
	v_fmac_f32_e32 v28, v44, v9
	v_fmac_f32_e32 v29, v45, v9
	v_fmac_f32_e32 v26, v58, v9
	v_fmac_f32_e32 v27, v48, v9
	v_fmac_f32_e32 v24, v50, v9
	v_fmac_f32_e32 v25, v52, v9
	v_fmac_f32_e32 v22, v63, v9
	v_fmac_f32_e32 v23, v57, v9
	v_fmac_f32_e32 v20, v57, v6
	v_fmac_f32_e32 v21, v57, v7
	v_fmac_f32_e32 v42, v57, v4
	v_fmac_f32_e32 v66, v63, v2
	s_waitcnt vmcnt(3)
	v_fmac_f32_e32 v80, v53, v6
	v_fmac_f32_e32 v81, v59, v6
	v_fmac_f32_e32 v30, v62, v6
	v_fmac_f32_e32 v31, v46, v6
	v_fmac_f32_e32 v28, v43, v6
	v_fmac_f32_e32 v29, v44, v6
	v_fmac_f32_e32 v26, v45, v6
	v_fmac_f32_e32 v27, v58, v6
	v_fmac_f32_e32 v24, v48, v6
	v_fmac_f32_e32 v25, v50, v6
	v_fmac_f32_e32 v22, v52, v6
	v_fmac_f32_e32 v23, v63, v6
	v_fmac_f32_e32 v20, v63, v7
	v_fmac_f32_e32 v21, v63, v4
	v_fmac_f32_e32 v42, v63, v5
	v_fmac_f32_e32 v66, v52, v3
	v_fmac_f32_e32 v80, v47, v7
	v_fmac_f32_e32 v81, v53, v7
	v_fmac_f32_e32 v30, v59, v7
	v_fmac_f32_e32 v31, v62, v7
	v_fmac_f32_e32 v28, v46, v7
	v_fmac_f32_e32 v29, v43, v7
	v_fmac_f32_e32 v26, v44, v7
	v_fmac_f32_e32 v27, v45, v7
	v_fmac_f32_e32 v24, v58, v7
	v_fmac_f32_e32 v25, v48, v7
	v_fmac_f32_e32 v22, v50, v7
	v_fmac_f32_e32 v23, v52, v7
	v_fmac_f32_e32 v20, v52, v4
	v_fmac_f32_e32 v21, v52, v5
	v_fmac_f32_e32 v42, v52, v2
	s_waitcnt lgkmcnt(13)
	v_fmac_f32_e32 v66, v50, v75
	s_waitcnt vmcnt(2)
	v_fmac_f32_e32 v80, v51, v4
	v_fmac_f32_e32 v81, v47, v4
	v_fmac_f32_e32 v30, v53, v4
	v_fmac_f32_e32 v31, v59, v4
	v_fmac_f32_e32 v28, v62, v4
	v_fmac_f32_e32 v29, v46, v4
	v_fmac_f32_e32 v26, v43, v4
	v_fmac_f32_e32 v27, v44, v4
	v_fmac_f32_e32 v24, v45, v4
	v_fmac_f32_e32 v25, v58, v4
	v_fmac_f32_e32 v22, v48, v4
	v_fmac_f32_e32 v23, v50, v4
	v_fmac_f32_e32 v20, v50, v5
	v_fmac_f32_e32 v21, v50, v2
	v_fmac_f32_e32 v42, v50, v3
	s_waitcnt lgkmcnt(12)
	v_fmac_f32_e32 v66, v48, v73
	s_waitcnt vmcnt(1)
	v_fmac_f32_e32 v80, v49, v5
	v_fmac_f32_e32 v81, v51, v5
	v_fmac_f32_e32 v30, v47, v5
	v_fmac_f32_e32 v31, v53, v5
	v_fmac_f32_e32 v28, v59, v5
	v_fmac_f32_e32 v29, v62, v5
	v_fmac_f32_e32 v26, v46, v5
	v_fmac_f32_e32 v27, v43, v5
	v_fmac_f32_e32 v24, v44, v5
	v_fmac_f32_e32 v25, v45, v5
	v_fmac_f32_e32 v22, v58, v5
	v_fmac_f32_e32 v23, v48, v5
	v_fmac_f32_e32 v20, v48, v2
	v_fmac_f32_e32 v21, v48, v3
	v_fmac_f32_e32 v42, v48, v75
	s_waitcnt lgkmcnt(11)
	v_fmac_f32_e32 v66, v58, v72
	s_waitcnt vmcnt(0)
	v_fmac_f32_e32 v80, v55, v2
	v_fmac_f32_e32 v81, v49, v2
	v_fmac_f32_e32 v30, v51, v2
	v_fmac_f32_e32 v31, v47, v2
	v_fmac_f32_e32 v28, v53, v2
	v_fmac_f32_e32 v29, v59, v2
	v_fmac_f32_e32 v26, v62, v2
	v_fmac_f32_e32 v27, v46, v2
	v_fmac_f32_e32 v24, v43, v2
	v_fmac_f32_e32 v25, v44, v2
	v_fmac_f32_e32 v22, v45, v2
	v_fmac_f32_e32 v23, v58, v2
	v_fmac_f32_e32 v20, v58, v3
	v_fmac_f32_e32 v21, v58, v75
	v_fmac_f32_e32 v42, v58, v73
	v_and_b32_e32 v2, 64, v178
	s_waitcnt lgkmcnt(10)
; __device__ __forceinline__ void conv_task(const Params& p_, int l, int task, unsigned char* lds) {
;     ...
;       for (int j = 0; j < 46; ++j) { const float u = us[j * 512 + tid];
; #pragma unroll
;           for (int t = 0; t < 16; ++t) { const int k = j - t; if (k >= 0 && k < 31) y[t] += w[k] * u; } }
; #pragma unroll
;       for (int t = 0; t < 16; ++t) ys[t * 512 + tid] = y[t]; }
;     __syncthreads();
	v_fmac_f32_e32 v66, v45, v71
	v_fmac_f32_e32 v23, v45, v3
	v_fmac_f32_e32 v20, v45, v75
	v_fmac_f32_e32 v21, v45, v73
	v_fmac_f32_e32 v42, v45, v72
	v_add_u32_e32 v8, 64, v2
	v_xor_b32_e32 v2, 1, v178
	s_waitcnt lgkmcnt(9)
	v_fmac_f32_e32 v66, v44, v70
	v_fmac_f32_e32 v22, v44, v3
	v_fmac_f32_e32 v23, v44, v75
	v_fmac_f32_e32 v20, v44, v73
	v_fmac_f32_e32 v21, v44, v72
	v_fmac_f32_e32 v42, v44, v71
	v_cmp_lt_i32_e32 vcc, v2, v8
	s_waitcnt lgkmcnt(8)
	v_fmac_f32_e32 v66, v43, v69
	v_fmac_f32_e32 v25, v43, v3
	v_fmac_f32_e32 v22, v43, v75
	v_fmac_f32_e32 v23, v43, v73
	v_fmac_f32_e32 v20, v43, v72
	v_fmac_f32_e32 v21, v43, v71
	v_fmac_f32_e32 v42, v43, v70
	v_cndmask_b32_e32 v2, v178, v2, vcc
	s_waitcnt lgkmcnt(7)
	v_fmac_f32_e32 v66, v46, v68
	v_fmac_f32_e32 v24, v46, v3
	v_fmac_f32_e32 v25, v46, v75
	v_fmac_f32_e32 v22, v46, v73
	v_fmac_f32_e32 v23, v46, v72
	v_fmac_f32_e32 v20, v46, v71
	v_fmac_f32_e32 v21, v46, v70
	v_fmac_f32_e32 v42, v46, v69
	v_lshlrev_b32_e32 v39, 2, v2
	v_xor_b32_e32 v2, 2, v178
	s_waitcnt lgkmcnt(6)
	v_fmac_f32_e32 v66, v62, v67
	v_fmac_f32_e32 v27, v62, v3
	v_fmac_f32_e32 v24, v62, v75
	v_fmac_f32_e32 v25, v62, v73
	v_fmac_f32_e32 v22, v62, v72
	v_fmac_f32_e32 v23, v62, v71
	v_fmac_f32_e32 v20, v62, v70
	v_fmac_f32_e32 v21, v62, v69
	v_fmac_f32_e32 v42, v62, v68
	v_cmp_lt_i32_e32 vcc, v2, v8
	s_waitcnt lgkmcnt(5)
	v_fmac_f32_e32 v66, v59, v79
	v_fmac_f32_e32 v26, v59, v3
	v_fmac_f32_e32 v27, v59, v75
	v_fmac_f32_e32 v24, v59, v73
	v_fmac_f32_e32 v25, v59, v72
	v_fmac_f32_e32 v22, v59, v71
	v_fmac_f32_e32 v23, v59, v70
	v_fmac_f32_e32 v20, v59, v69
	v_fmac_f32_e32 v21, v59, v68
	v_fmac_f32_e32 v42, v59, v67
	v_cndmask_b32_e32 v2, v178, v2, vcc
	s_waitcnt lgkmcnt(4)
	v_fmac_f32_e32 v66, v53, v78
	v_fmac_f32_e32 v29, v53, v3
	v_fmac_f32_e32 v26, v53, v75
	v_fmac_f32_e32 v27, v53, v73
	v_fmac_f32_e32 v24, v53, v72
	v_fmac_f32_e32 v25, v53, v71
	v_fmac_f32_e32 v22, v53, v70
	v_fmac_f32_e32 v23, v53, v69
	v_fmac_f32_e32 v20, v53, v68
	v_fmac_f32_e32 v21, v53, v67
	v_fmac_f32_e32 v42, v53, v79
	v_lshlrev_b32_e32 v40, 2, v2
	v_xor_b32_e32 v2, 4, v178
	s_waitcnt lgkmcnt(3)
	v_fmac_f32_e32 v66, v47, v77
	v_fmac_f32_e32 v28, v47, v3
	v_fmac_f32_e32 v29, v47, v75
	v_fmac_f32_e32 v26, v47, v73
	v_fmac_f32_e32 v27, v47, v72
	v_fmac_f32_e32 v24, v47, v71
	v_fmac_f32_e32 v25, v47, v70
	v_fmac_f32_e32 v22, v47, v69
	v_fmac_f32_e32 v23, v47, v68
	v_fmac_f32_e32 v20, v47, v67
	v_fmac_f32_e32 v21, v47, v79
	v_fmac_f32_e32 v42, v47, v78
	v_cmp_lt_i32_e32 vcc, v2, v8
	s_waitcnt lgkmcnt(2)
	v_fmac_f32_e32 v66, v51, v76
	v_fmac_f32_e32 v31, v51, v3
	v_fmac_f32_e32 v28, v51, v75
	v_fmac_f32_e32 v29, v51, v73
	v_fmac_f32_e32 v26, v51, v72
	v_fmac_f32_e32 v27, v51, v71
	v_fmac_f32_e32 v24, v51, v70
	v_fmac_f32_e32 v25, v51, v69
	v_fmac_f32_e32 v22, v51, v68
	v_fmac_f32_e32 v23, v51, v67
	v_fmac_f32_e32 v20, v51, v79
	v_fmac_f32_e32 v21, v51, v78
	v_fmac_f32_e32 v42, v51, v77
	v_cndmask_b32_e32 v2, v178, v2, vcc
	s_waitcnt lgkmcnt(1)
	v_fmac_f32_e32 v66, v49, v74
	v_fmac_f32_e32 v81, v55, v3
	v_fmac_f32_e32 v30, v49, v3
	v_fmac_f32_e32 v31, v49, v75
	v_fmac_f32_e32 v28, v49, v73
	v_fmac_f32_e32 v29, v49, v72
	v_fmac_f32_e32 v26, v49, v71
	v_fmac_f32_e32 v27, v49, v70
	v_fmac_f32_e32 v24, v49, v69
	v_fmac_f32_e32 v25, v49, v68
	v_fmac_f32_e32 v22, v49, v67
	v_fmac_f32_e32 v23, v49, v79
	v_fmac_f32_e32 v20, v49, v78
	v_fmac_f32_e32 v21, v49, v77
	v_fmac_f32_e32 v42, v49, v76
	v_and_b32_e32 v38, 63, v54
	v_add_u32_e32 v0, s6, v60
	v_lshlrev_b32_e32 v41, 2, v2
	v_xor_b32_e32 v2, 8, v178
	s_waitcnt lgkmcnt(0)
	v_fmac_f32_e32 v66, v55, v82
	v_fmac_f32_e32 v30, v55, v75
	v_fmac_f32_e32 v31, v55, v73
	v_fmac_f32_e32 v28, v55, v72
	v_fmac_f32_e32 v29, v55, v71
	v_fmac_f32_e32 v26, v55, v70
	v_fmac_f32_e32 v27, v55, v69
	v_fmac_f32_e32 v24, v55, v68
	v_fmac_f32_e32 v25, v55, v67
	v_fmac_f32_e32 v22, v55, v79
	v_fmac_f32_e32 v23, v55, v78
	v_fmac_f32_e32 v20, v55, v77
	v_fmac_f32_e32 v21, v55, v76
	v_fmac_f32_e32 v42, v55, v74
	ds_write2st64_b32 v0, v80, v81 offset1:8
	ds_write2st64_b32 v0, v30, v31 offset0:16 offset1:24
	ds_write2st64_b32 v0, v28, v29 offset0:32 offset1:40
	ds_write2st64_b32 v0, v26, v27 offset0:48 offset1:56
	ds_write2st64_b32 v0, v24, v25 offset0:64 offset1:72
	ds_write2st64_b32 v0, v22, v23 offset0:80 offset1:88
	ds_write2st64_b32 v0, v20, v21 offset0:96 offset1:104
	ds_write2st64_b32 v0, v42, v66 offset0:112 offset1:120
	v_lshl_add_u32 v0, v38, 2, s6
	v_cmp_lt_i32_e32 vcc, v2, v8
	v_add_u32_e32 v43, 8, v56
	v_lshl_add_u32 v9, v56, 11, v0
	v_cndmask_b32_e32 v2, v178, v2, vcc
	v_lshl_add_u32 v0, v43, 11, v0
	s_waitcnt lgkmcnt(0)
	s_barrier
; __device__ __forceinline__ void conv_task(const Params& p_, int l, int task, unsigned char* lds) {
;     ...
;     for (int tw = 0; tw < 2; ++tw) { const int t = wave + 8 * tw; float v[8]; float s = 0.f;
; #pragma unroll
;         for (int j = 0; j < 8; ++j) { v[j] = ys[t * 512 + lane + 64 * j]; s += v[j]; }
;         const float mu = wave_sum(s) * (1.f / 512.f); float q = 0.f;
; #pragma unroll
;         for (int j = 0; j < 8; ++j) { v[j] -= mu; q += v[j] * v[j]; }
;         const float rstd = rsqrtf(wave_sum(q) * (1.f / 512.f) + 1e-6f);
	v_lshlrev_b32_e32 v42, 2, v2
	ds_read2st64_b32 v[2:3], v9 offset0:4 offset1:5
	ds_read2st64_b32 v[4:5], v9 offset1:1
	ds_read2st64_b32 v[6:7], v9 offset0:6 offset1:7
	ds_read2st64_b32 v[16:17], v9 offset0:2 offset1:3
	ds_read2st64_b32 v[10:11], v0 offset1:1
	ds_read2st64_b32 v[14:15], v0 offset0:2 offset1:3
	ds_read2st64_b32 v[18:19], v0 offset0:4 offset1:5
	ds_read2st64_b32 v[20:21], v0 offset0:6 offset1:7
	s_waitcnt lgkmcnt(6)
	v_mov_b32_e32 v23, v4
	v_mov_b32_e32 v9, v2
	s_waitcnt lgkmcnt(5)
	v_mov_b32_e32 v13, v6
	s_waitcnt lgkmcnt(3)
	v_mov_b32_e32 v22, v10
	v_pk_add_f32 v[24:25], v[22:23], 0 op_sel_hi:[1,0]
	v_mov_b32_e32 v4, v11
	v_pk_add_f32 v[10:11], v[24:25], v[4:5]
	s_waitcnt lgkmcnt(2)
	v_mov_b32_e32 v24, v14
	v_mov_b32_e32 v25, v16
	v_pk_add_f32 v[10:11], v[10:11], v[24:25]
	v_mov_b32_e32 v16, v15
	v_pk_add_f32 v[10:11], v[10:11], v[16:17]
	s_waitcnt lgkmcnt(1)
	v_mov_b32_e32 v14, v18
	v_mov_b32_e32 v15, v2
	v_pk_add_f32 v[10:11], v[10:11], v[14:15]
	v_mov_b32_e32 v2, v19
	v_pk_add_f32 v[10:11], v[10:11], v[2:3]
	s_waitcnt lgkmcnt(0)
	v_mov_b32_e32 v14, v20
	v_mov_b32_e32 v15, v6
	v_pk_add_f32 v[10:11], v[10:11], v[14:15]
	v_mov_b32_e32 v6, v21
	v_pk_add_f32 v[10:11], v[10:11], v[6:7]
	s_nop 1
	v_mov_b32_dpp v15, v11 quad_perm:[1,0,3,2] row_mask:0xf bank_mask:0xf
	v_mov_b32_dpp v14, v10 quad_perm:[1,0,3,2] row_mask:0xf bank_mask:0xf
	v_xor_b32_e32 v12, 16, v178
	v_cmp_lt_i32_e32 vcc, v12, v8
	v_mov_b32_e32 v30, v19
	v_mov_b32_e32 v31, v18
	s_waitcnt lgkmcnt(0)
	v_pk_add_f32 v[10:11], v[10:11], v[14:15]
	s_nop 1
	v_mov_b32_dpp v15, v11 quad_perm:[2,3,0,1] row_mask:0xf bank_mask:0xf
	v_mov_b32_dpp v14, v10 quad_perm:[2,3,0,1] row_mask:0xf bank_mask:0xf
	v_cndmask_b32_e32 v0, v178, v12, vcc
	v_lshlrev_b32_e32 v44, 2, v0
	v_xor_b32_e32 v0, 32, v178
	v_cmp_lt_i32_e32 vcc, v0, v8
	v_mov_b32_e32 v8, v3
	s_waitcnt lgkmcnt(0)
	v_pk_add_f32 v[2:3], v[10:11], v[14:15]
	s_nop 1
	v_mov_b32_dpp v11, v3 row_half_mirror row_mask:0xf bank_mask:0xf
	v_mov_b32_dpp v10, v2 row_half_mirror row_mask:0xf bank_mask:0xf
	v_cndmask_b32_e32 v0, v178, v0, vcc
	v_lshlrev_b32_e32 v45, 2, v0
	v_or_b32_e32 v0, s3, v38
	v_mov_b32_e32 v12, v7
	s_waitcnt lgkmcnt(0)
	v_pk_add_f32 v[2:3], v[2:3], v[10:11]
	s_nop 1
	v_mov_b32_dpp v11, v3 row_mirror row_mask:0xf bank_mask:0xf
	v_mov_b32_dpp v10, v2 row_mirror row_mask:0xf bank_mask:0xf
	v_lshlrev_b64 v[6:7], 2, v[0:1]
	v_lshl_add_u64 v[14:15], s[60:61], 0, v[6:7]
	v_lshl_add_u64 v[6:7], s[62:63], 0, v[6:7]
	global_load_dword v46, v[14:15], off
	global_load_dword v47, v[6:7], off
	s_waitcnt lgkmcnt(0)
	v_pk_add_f32 v[2:3], v[2:3], v[10:11]
	v_mov_b32_e32 v11, v3
	v_mov_b32_e32 v10, v2
	s_nop 1
	v_permlane16_swap_b32_e32 v3, v11
	v_permlane16_swap_b32_e32 v2, v10
	v_add_u32_e32 v6, s3, v38
	v_mov_b32_e32 v7, v1
	v_lshlrev_b64 v[6:7], 2, v[6:7]
	v_lshl_add_u64 v[26:27], s[60:61], 0, v[6:7]
	s_waitcnt lgkmcnt(0)
	v_pk_add_f32 v[2:3], v[2:3], v[10:11]
	v_mov_b32_e32 v11, v3
	v_mov_b32_e32 v10, v2
	s_nop 1
	v_permlane32_swap_b32_e32 v3, v11
	v_permlane32_swap_b32_e32 v2, v10
	global_load_dword v48, v[26:27], off offset:256
	v_lshl_add_u64 v[28:29], s[62:63], 0, v[6:7]
	global_load_dword v49, v[28:29], off offset:256
	s_waitcnt lgkmcnt(0)
	v_pk_add_f32 v[2:3], v[2:3], v[10:11]
	s_nop 0
	v_pk_mul_f32 v[18:19], v[2:3], s[2:3] op_sel_hi:[1,0]
	v_pk_fma_f32 v[10:11], v[2:3], s[2:3], v[4:5] op_sel_hi:[1,0,1] neg_lo:[1,0,0] neg_hi:[1,0,0]
	v_pk_add_f32 v[14:15], v[12:13], v[18:19] op_sel:[0,1] neg_lo:[0,1] neg_hi:[0,1]
	v_pk_fma_f32 v[12:13], v[2:3], s[2:3], v[22:23] op_sel_hi:[1,0,1] neg_lo:[1,0,0] neg_hi:[1,0,0]
	v_pk_mul_f32 v[4:5], v[10:11], v[10:11]
	v_pk_add_f32 v[32:33], v[8:9], v[18:19] op_sel:[0,1] neg_lo:[0,1] neg_hi:[0,1]
	v_pk_fma_f32 v[4:5], v[12:13], v[12:13], v[4:5]
	v_pk_fma_f32 v[8:9], v[2:3], s[2:3], v[24:25] op_sel_hi:[1,0,1] neg_lo:[1,0,0] neg_hi:[1,0,0]
	v_pk_fma_f32 v[6:7], v[2:3], s[2:3], v[16:17] op_sel_hi:[1,0,1] neg_lo:[1,0,0] neg_hi:[1,0,0]
	v_pk_fma_f32 v[4:5], v[8:9], v[8:9], v[4:5]
	v_pk_mul_f32 v[34:35], v[32:33], v[32:33]
	v_pk_fma_f32 v[2:3], v[6:7], v[6:7], v[4:5]
	v_pk_add_f32 v[4:5], v[30:31], v[18:19] op_sel_hi:[1,0] neg_lo:[0,1] neg_hi:[0,1]
	v_mov_b32_e32 v23, v35
	v_pk_mul_f32 v[16:17], v[4:5], v[4:5]
	v_pk_mul_f32 v[36:37], v[14:15], v[14:15]
	v_mov_b32_e32 v22, v17
	v_pk_add_f32 v[22:23], v[22:23], v[2:3]
	v_mov_b32_e32 v2, v21
	v_mov_b32_e32 v3, v20
	v_pk_add_f32 v[2:3], v[2:3], v[18:19] op_sel_hi:[1,0] neg_lo:[0,1] neg_hi:[0,1]
	v_mov_b32_e32 v17, v34
	v_pk_mul_f32 v[18:19], v[2:3], v[2:3]
	v_pk_add_f32 v[16:17], v[16:17], v[22:23]
	v_mov_b32_e32 v20, v19
	v_mov_b32_e32 v21, v37
	v_pk_add_f32 v[16:17], v[20:21], v[16:17]
	v_mov_b32_e32 v19, v36
	v_pk_add_f32 v[16:17], v[18:19], v[16:17]
	s_nop 1
	v_mov_b32_dpp v19, v17 quad_perm:[1,0,3,2] row_mask:0xf bank_mask:0xf
	v_mov_b32_dpp v18, v16 quad_perm:[1,0,3,2] row_mask:0xf bank_mask:0xf
	global_load_dword v22, v[26:27], off offset:512
	global_load_dword v23, v[28:29], off offset:512
	global_load_dword v24, v[26:27], off offset:768
	global_load_dword v25, v[28:29], off offset:768
	v_add_u32_e32 v20, s68, v56
	v_ashrrev_i32_e32 v21, 31, v20
	s_waitcnt lgkmcnt(0)
	v_pk_add_f32 v[16:17], v[16:17], v[18:19]
	s_nop 1
	v_mov_b32_dpp v19, v17 quad_perm:[2,3,0,1] row_mask:0xf bank_mask:0xf
	v_mov_b32_dpp v18, v16 quad_perm:[2,3,0,1] row_mask:0xf bank_mask:0xf
	v_lshlrev_b64 v[20:21], 10, v[20:21]
	v_lshl_add_u64 v[20:21], s[40:41], 0, v[20:21]
	s_waitcnt lgkmcnt(0)
	v_pk_add_f32 v[16:17], v[16:17], v[18:19]
	s_nop 1
	v_mov_b32_dpp v19, v17 row_half_mirror row_mask:0xf bank_mask:0xf
	v_mov_b32_dpp v18, v16 row_half_mirror row_mask:0xf bank_mask:0xf
	s_waitcnt lgkmcnt(0)
; __device__ __forceinline__ unsigned f2bf(float f) { unsigned u = __float_as_uint(f); return (u + 0x7fffu + ((u >> 16) & 1u)) >> 16; }
; __device__ __forceinline__ float silu_f(float v) { return v / (1.f + __expf(-v)); }
; __device__ __forceinline__ void conv_task(const Params& p_, int l, int task, unsigned char* lds) {
;     ...
;         const float mu = wave_sum(s) * (1.f / 512.f); float q = 0.f;
; #pragma unroll
;         for (int j = 0; j < 8; ++j) { v[j] -= mu; q += v[j] * v[j]; }
;         const float rstd = rsqrtf(wave_sum(q) * (1.f / 512.f) + 1e-6f);
;         bf16* orow = (bf16*)(p.ws + WS_CVH) + (size_t)(b * SEQ + t0 + t) * DG;
; #pragma unroll
;         for (int j = 0; j < 8; ++j) { const int ch = lane + 64 * j; const float y = v[j] * rstd * p.ln_g[l * DG + ch] + p.ln_b[l * DG + ch]; orow[ch] = (bf16)f2bf(silu_f(y)); } }
	v_pk_add_f32 v[16:17], v[16:17], v[18:19]
	s_nop 1
	v_mov_b32_dpp v19, v17 row_mirror row_mask:0xf bank_mask:0xf
	v_mov_b32_dpp v18, v16 row_mirror row_mask:0xf bank_mask:0xf
	s_waitcnt lgkmcnt(0)
	v_pk_add_f32 v[16:17], v[16:17], v[18:19]
	v_mov_b32_e32 v19, v17
	v_mov_b32_e32 v18, v16
	s_nop 1
	v_permlane16_swap_b32_e32 v17, v19
	v_permlane16_swap_b32_e32 v16, v18
	s_waitcnt lgkmcnt(0)
	v_pk_add_f32 v[16:17], v[16:17], v[18:19]
	v_mov_b32_e32 v19, v17
	v_mov_b32_e32 v18, v16
	s_nop 1
	v_permlane32_swap_b32_e32 v17, v19
	v_permlane32_swap_b32_e32 v16, v18
	s_waitcnt lgkmcnt(0)
	v_pk_add_f32 v[16:17], v[16:17], v[18:19]
	s_nop 0
	v_pk_fma_f32 v[16:17], v[16:17], s[2:3], v[146:147] op_sel_hi:[1,0,0]
	s_nop 0
	v_mul_f32_e32 v0, 0x4b800000, v17
	v_cmp_gt_f32_e32 vcc, s92, v17
	v_cmp_gt_f32_e64 s[36:37], s92, v16
	s_nop 0
	v_cndmask_b32_e32 v0, v17, v0, vcc
	v_rsq_f32_e32 v17, v0
	v_lshlrev_b32_e32 v0, 1, v38
	v_lshl_add_u64 v[18:19], v[20:21], 0, v[0:1]
	global_load_dword v20, v[28:29], off offset:1024
	global_load_dword v30, v[26:27], off offset:1024
	global_load_dword v31, v[26:27], off offset:1280
	global_load_dword v34, v[26:27], off offset:1536
	s_nop 0
	global_load_dword v26, v[26:27], off offset:1792
	v_mul_f32_e32 v21, 0x45800000, v17
	v_cndmask_b32_e32 v17, v17, v21, vcc
	v_mul_f32_e32 v13, v13, v17
	s_waitcnt vmcnt(11)
	v_fma_f32 v13, v46, v13, v47
	v_mul_f32_e32 v21, 0xbfb8aa3b, v13
	v_exp_f32_e32 v21, v21
	global_load_dword v36, v[28:29], off offset:1280
	global_load_dword v37, v[28:29], off offset:1536
	s_nop 0
	global_load_dword v28, v[28:29], off offset:1792
	v_mul_f32_e32 v11, v11, v17
	s_waitcnt vmcnt(12)
	v_fma_f32 v11, v48, v11, v49
	v_add_f32_e32 v21, 1.0, v21
	v_div_scale_f32 v27, s[12:13], v21, v21, v13
	v_rcp_f32_e32 v35, v27
	v_mul_f32_e32 v9, v9, v17
	v_mul_f32_e32 v7, v7, v17
	v_fma_f32 v29, -v27, v35, 1.0
	v_fmac_f32_e32 v35, v29, v35
	v_div_scale_f32 v29, vcc, v13, v21, v13
	v_mul_f32_e32 v38, v29, v35
	v_fma_f32 v39, -v27, v38, v29
	v_fmac_f32_e32 v38, v39, v35
	v_fma_f32 v27, -v27, v38, v29
	v_mul_f32_e32 v29, 0xbfb8aa3b, v11
	v_exp_f32_e32 v29, v29
	v_div_fmas_f32 v27, v27, v35, v38
	v_div_fixup_f32 v13, v27, v21, v13
	v_bfe_u32 v35, v13, 16, 1
	v_add_f32_e32 v21, 1.0, v29
	v_div_scale_f32 v27, s[12:13], v21, v21, v11
	v_rcp_f32_e32 v29, v27
	v_add3_u32 v13, v13, v35, s14
	global_store_short_d16_hi v[18:19], v13, off
	s_waitcnt vmcnt(11)
	v_fma_f32 v9, v22, v9, v23
	v_fma_f32 v13, -v27, v29, 1.0
	v_fmac_f32_e32 v29, v13, v29
	v_div_scale_f32 v13, vcc, v11, v21, v11
	v_mul_f32_e32 v35, v13, v29
	v_fma_f32 v38, -v27, v35, v13
	v_fmac_f32_e32 v35, v38, v29
	v_fma_f32 v13, -v27, v35, v13
	v_mul_f32_e32 v27, 0xbfb8aa3b, v9
	v_exp_f32_e32 v27, v27
	v_div_fmas_f32 v13, v13, v29, v35
	v_div_fixup_f32 v11, v13, v21, v11
	v_bfe_u32 v29, v11, 16, 1
	v_add_f32_e32 v13, 1.0, v27
	v_div_scale_f32 v21, s[12:13], v13, v13, v9
	v_rcp_f32_e32 v27, v21
	v_add3_u32 v11, v11, v29, s14
	global_store_short_d16_hi v[18:19], v11, off offset:128
	s_waitcnt vmcnt(10)
	v_fma_f32 v7, v24, v7, v25
	v_fma_f32 v11, -v21, v27, 1.0
	v_fmac_f32_e32 v27, v11, v27
	v_div_scale_f32 v11, vcc, v9, v13, v9
	v_mul_f32_e32 v29, v11, v27
	v_fma_f32 v35, -v21, v29, v11
	v_fmac_f32_e32 v29, v35, v27
	v_fma_f32 v11, -v21, v29, v11
	v_mul_f32_e32 v21, 0xbfb8aa3b, v7
	v_exp_f32_e32 v21, v21
	v_div_fmas_f32 v11, v11, v27, v29
	v_div_fixup_f32 v9, v11, v13, v9
	v_bfe_u32 v27, v9, 16, 1
	v_add_f32_e32 v11, 1.0, v21
	v_div_scale_f32 v13, s[12:13], v11, v11, v7
	v_rcp_f32_e32 v21, v13
	v_add3_u32 v9, v9, v27, s14
	global_store_short_d16_hi v[18:19], v9, off offset:256
	v_fma_f32 v9, -v13, v21, 1.0
	v_fmac_f32_e32 v21, v9, v21
	v_div_scale_f32 v9, vcc, v7, v11, v7
	v_mul_f32_e32 v27, v9, v21
	v_fma_f32 v29, -v13, v27, v9
	v_fmac_f32_e32 v27, v29, v21
	v_fma_f32 v9, -v13, v27, v9
	v_mul_f32_e32 v13, v33, v17
	s_waitcnt vmcnt(9)
	v_fma_f32 v13, v30, v13, v20
	v_mul_f32_e32 v29, 0xbfb8aa3b, v13
	v_exp_f32_e32 v29, v29
	v_div_fmas_f32 v9, v9, v21, v27
	v_div_fixup_f32 v7, v9, v11, v7
	v_bfe_u32 v27, v7, 16, 1
	v_add_f32_e32 v9, 1.0, v29
	v_div_scale_f32 v11, s[12:13], v9, v9, v13
	v_rcp_f32_e32 v21, v11
	v_add3_u32 v7, v7, v27, s14
	global_store_short_d16_hi v[18:19], v7, off offset:384
	v_fma_f32 v7, -v11, v21, 1.0
	v_fmac_f32_e32 v21, v7, v21
	v_div_scale_f32 v7, vcc, v13, v9, v13
	v_mul_f32_e32 v27, v7, v21
	v_fma_f32 v29, -v11, v27, v7
	v_fmac_f32_e32 v27, v29, v21
	v_fma_f32 v7, -v11, v27, v7
	v_mul_f32_e32 v11, v32, v17
	s_waitcnt vmcnt(6)
	v_fma_f32 v11, v31, v11, v36
	v_mul_f32_e32 v29, 0xbfb8aa3b, v11
	v_exp_f32_e32 v29, v29
	v_div_fmas_f32 v7, v7, v21, v27
	v_div_fixup_f32 v7, v7, v9, v13
	v_bfe_u32 v27, v7, 16, 1
	v_add_f32_e32 v9, 1.0, v29
	v_div_scale_f32 v13, s[12:13], v9, v9, v11
	v_rcp_f32_e32 v21, v13
	v_add3_u32 v7, v7, v27, s14
	global_store_short_d16_hi v[18:19], v7, off offset:512
	v_fma_f32 v7, -v13, v21, 1.0
	v_fmac_f32_e32 v21, v7, v21
	v_div_scale_f32 v7, vcc, v11, v9, v11
	v_mul_f32_e32 v27, v7, v21
	v_fma_f32 v29, -v13, v27, v7
	v_fmac_f32_e32 v27, v29, v21
	v_fma_f32 v7, -v13, v27, v7
	v_mul_f32_e32 v13, v15, v17
	s_waitcnt vmcnt(6)
	v_fma_f32 v13, v34, v13, v37
	v_mul_f32_e32 v15, 0xbfb8aa3b, v13
	v_exp_f32_e32 v15, v15
	v_div_fmas_f32 v7, v7, v21, v27
	v_div_fixup_f32 v7, v7, v9, v11
	v_bfe_u32 v21, v7, 16, 1
	v_add_f32_e32 v9, 1.0, v15
	v_div_scale_f32 v11, s[12:13], v9, v9, v13
	v_rcp_f32_e32 v15, v11
	v_add3_u32 v7, v7, v21, s14
	global_store_short_d16_hi v[18:19], v7, off offset:640
	v_fma_f32 v7, -v11, v15, 1.0
	v_fmac_f32_e32 v15, v7, v15
	v_div_scale_f32 v7, vcc, v13, v9, v13
	v_mul_f32_e32 v21, v7, v15
	v_fma_f32 v27, -v11, v21, v7
	v_fmac_f32_e32 v21, v27, v15
	v_fma_f32 v7, -v11, v21, v7
	v_mul_f32_e32 v11, v14, v17
	s_waitcnt vmcnt(6)
; __device__ __forceinline__ unsigned f2bf(float f) { unsigned u = __float_as_uint(f); return (u + 0x7fffu + ((u >> 16) & 1u)) >> 16; }
; __device__ __forceinline__ float silu_f(float v) { return v / (1.f + __expf(-v)); }
; __device__ __forceinline__ void conv_task(const Params& p_, int l, int task, unsigned char* lds) {
;     ...
;     for (int tw = 0; tw < 2; ++tw) { const int t = wave + 8 * tw; float v[8]; float s = 0.f;
; #pragma unroll
;         for (int j = 0; j < 8; ++j) { v[j] = ys[t * 512 + lane + 64 * j]; s += v[j]; }
;         const float mu = wave_sum(s) * (1.f / 512.f); float q = 0.f;
; #pragma unroll
;         for (int j = 0; j < 8; ++j) { v[j] -= mu; q += v[j] * v[j]; }
;         const float rstd = rsqrtf(wave_sum(q) * (1.f / 512.f) + 1e-6f);
;         bf16* orow = (bf16*)(p.ws + WS_CVH) + (size_t)(b * SEQ + t0 + t) * DG;
; #pragma unroll
;         for (int j = 0; j < 8; ++j) { const int ch = lane + 64 * j; const float y = v[j] * rstd * p.ln_g[l * DG + ch] + p.ln_b[l * DG + ch]; orow[ch] = (bf16)f2bf(silu_f(y)); } }
;     __syncthreads();
	v_fma_f32 v11, v11, v26, v28
	v_mul_f32_e32 v14, 0xbfb8aa3b, v11
	v_exp_f32_e32 v14, v14
	v_div_fmas_f32 v7, v7, v15, v21
	v_div_fixup_f32 v7, v7, v9, v13
	v_bfe_u32 v15, v7, 16, 1
	v_add_f32_e32 v9, 1.0, v14
	v_div_scale_f32 v13, s[12:13], v9, v9, v11
	v_rcp_f32_e32 v14, v13
	v_add3_u32 v7, v7, v15, s14
	global_store_short_d16_hi v[18:19], v7, off offset:768
	v_fma_f32 v7, -v13, v14, 1.0
	v_fmac_f32_e32 v14, v7, v14
	v_div_scale_f32 v7, vcc, v11, v9, v11
	v_mul_f32_e32 v15, v7, v14
	v_fma_f32 v17, -v13, v15, v7
	v_fmac_f32_e32 v15, v17, v14
	v_fma_f32 v7, -v13, v15, v7
	v_mul_f32_e32 v13, 0x4b800000, v16
	v_cndmask_b32_e64 v13, v16, v13, s[36:37]
	v_rsq_f32_e32 v13, v13
	v_div_fmas_f32 v7, v7, v14, v15
	v_div_fixup_f32 v7, v7, v9, v11
	v_bfe_u32 v9, v7, 16, 1
	v_mul_f32_e32 v11, 0x45800000, v13
	v_cndmask_b32_e64 v14, v13, v11, s[36:37]
	v_mul_f32_e32 v11, v12, v14
	v_fmac_f32_e32 v47, v46, v11
	v_mul_f32_e32 v11, 0xbfb8aa3b, v47
	v_exp_f32_e32 v11, v11
	v_add3_u32 v7, v7, v9, s14
	global_store_short_d16_hi v[18:19], v7, off offset:896
	v_mul_f32_e32 v10, v10, v14
	v_add_f32_e32 v7, 1.0, v11
	v_div_scale_f32 v9, s[12:13], v7, v7, v47
	v_rcp_f32_e32 v11, v9
	v_fmac_f32_e32 v49, v48, v10
	v_mul_f32_e32 v10, 0xbfb8aa3b, v49
	v_exp_f32_e32 v10, v10
	v_fma_f32 v15, -v9, v11, 1.0
	v_fmac_f32_e32 v11, v15, v11
	v_div_scale_f32 v15, vcc, v47, v7, v47
	v_mul_f32_e32 v16, v15, v11
	v_fma_f32 v17, -v9, v16, v15
	v_fmac_f32_e32 v16, v17, v11
	v_fma_f32 v9, -v9, v16, v15
	v_add_f32_e32 v15, 1.0, v10
	v_div_fmas_f32 v9, v9, v11, v16
	v_div_scale_f32 v16, s[12:13], v15, v15, v49
	v_add_u32_e32 v12, s68, v43
	v_rcp_f32_e32 v17, v16
	v_ashrrev_i32_e32 v13, 31, v12
	v_lshlrev_b64 v[12:13], 10, v[12:13]
	v_lshl_add_u64 v[12:13], s[40:41], 0, v[12:13]
	v_div_fixup_f32 v7, v9, v7, v47
	v_mul_f32_e32 v8, v8, v14
	v_bfe_u32 v9, v7, 16, 1
	v_lshl_add_u64 v[10:11], v[12:13], 0, v[0:1]
	v_fma_f32 v0, -v16, v17, 1.0
	v_fmac_f32_e32 v23, v22, v8
	v_add3_u32 v7, v7, v9, s14
	v_fmac_f32_e32 v17, v0, v17
	v_div_scale_f32 v0, vcc, v49, v15, v49
	v_mul_f32_e32 v8, 0xbfb8aa3b, v23
	global_store_short_d16_hi v[10:11], v7, off
	v_mul_f32_e32 v7, v0, v17
	v_exp_f32_e32 v8, v8
	v_fma_f32 v9, -v16, v7, v0
	v_fmac_f32_e32 v7, v9, v17
	v_fma_f32 v0, -v16, v7, v0
	v_div_fmas_f32 v0, v0, v17, v7
	v_add_f32_e32 v7, 1.0, v8
	v_div_scale_f32 v8, s[12:13], v7, v7, v23
	v_rcp_f32_e32 v9, v8
	v_div_fixup_f32 v0, v0, v15, v49
	v_bfe_u32 v12, v0, 16, 1
	v_add3_u32 v0, v0, v12, s14
	v_mul_f32_e32 v6, v6, v14
	global_store_short_d16_hi v[10:11], v0, off offset:128
	v_fma_f32 v0, -v8, v9, 1.0
	v_fmac_f32_e32 v25, v24, v6
	v_fmac_f32_e32 v9, v0, v9
	v_div_scale_f32 v0, vcc, v23, v7, v23
	v_mul_f32_e32 v6, 0xbfb8aa3b, v25
	v_mul_f32_e32 v12, v0, v9
	v_exp_f32_e32 v6, v6
	v_fma_f32 v13, -v8, v12, v0
	v_fmac_f32_e32 v12, v13, v9
	v_fma_f32 v0, -v8, v12, v0
	v_div_fmas_f32 v0, v0, v9, v12
	v_add_f32_e32 v6, 1.0, v6
	v_div_fixup_f32 v0, v0, v7, v23
	v_div_scale_f32 v7, s[12:13], v6, v6, v25
	v_rcp_f32_e32 v8, v7
	v_bfe_u32 v9, v0, 16, 1
	v_add3_u32 v0, v0, v9, s14
	v_mul_f32_e32 v5, v5, v14
	global_store_short_d16_hi v[10:11], v0, off offset:256
	v_fma_f32 v0, -v7, v8, 1.0
	v_fmac_f32_e32 v20, v30, v5
	v_fmac_f32_e32 v8, v0, v8
	v_div_scale_f32 v0, vcc, v25, v6, v25
	v_mul_f32_e32 v5, 0xbfb8aa3b, v20
	v_mul_f32_e32 v9, v0, v8
	v_exp_f32_e32 v5, v5
	v_fma_f32 v12, -v7, v9, v0
	v_fmac_f32_e32 v9, v12, v8
	v_fma_f32 v0, -v7, v9, v0
	v_div_fmas_f32 v0, v0, v8, v9
	v_add_f32_e32 v5, 1.0, v5
	v_div_fixup_f32 v0, v0, v6, v25
	v_div_scale_f32 v6, s[12:13], v5, v5, v20
	v_rcp_f32_e32 v7, v6
	v_bfe_u32 v8, v0, 16, 1
	v_add3_u32 v0, v0, v8, s14
	v_mul_f32_e32 v4, v4, v14
	global_store_short_d16_hi v[10:11], v0, off offset:384
	v_fma_f32 v0, -v6, v7, 1.0
	v_fmac_f32_e32 v36, v31, v4
	v_fmac_f32_e32 v7, v0, v7
	v_div_scale_f32 v0, vcc, v20, v5, v20
	v_mul_f32_e32 v4, 0xbfb8aa3b, v36
	v_mul_f32_e32 v8, v0, v7
	v_exp_f32_e32 v4, v4
	v_fma_f32 v9, -v6, v8, v0
	v_fmac_f32_e32 v8, v9, v7
	v_fma_f32 v0, -v6, v8, v0
	v_div_fmas_f32 v0, v0, v7, v8
	v_add_f32_e32 v4, 1.0, v4
	v_div_fixup_f32 v0, v0, v5, v20
	v_div_scale_f32 v5, s[12:13], v4, v4, v36
	v_rcp_f32_e32 v6, v5
	v_bfe_u32 v7, v0, 16, 1
	v_add3_u32 v0, v0, v7, s14
	v_mul_f32_e32 v3, v3, v14
	global_store_short_d16_hi v[10:11], v0, off offset:512
	v_fma_f32 v0, -v5, v6, 1.0
	v_fmac_f32_e32 v37, v34, v3
	v_fmac_f32_e32 v6, v0, v6
	v_div_scale_f32 v0, vcc, v36, v4, v36
	v_mul_f32_e32 v3, 0xbfb8aa3b, v37
	v_mul_f32_e32 v7, v0, v6
	v_exp_f32_e32 v3, v3
	v_fma_f32 v8, -v5, v7, v0
	v_fmac_f32_e32 v7, v8, v6
	v_fma_f32 v0, -v5, v7, v0
	v_div_fmas_f32 v0, v0, v6, v7
	v_add_f32_e32 v3, 1.0, v3
	v_div_fixup_f32 v0, v0, v4, v36
	v_div_scale_f32 v4, s[12:13], v3, v3, v37
	v_rcp_f32_e32 v5, v4
	v_bfe_u32 v6, v0, 16, 1
	v_add3_u32 v0, v0, v6, s14
	v_mul_f32_e32 v2, v2, v14
	global_store_short_d16_hi v[10:11], v0, off offset:640
	v_fma_f32 v0, -v4, v5, 1.0
	v_fmac_f32_e32 v28, v26, v2
	v_fmac_f32_e32 v5, v0, v5
	v_div_scale_f32 v0, vcc, v37, v3, v37
	v_mul_f32_e32 v2, 0xbfb8aa3b, v28
	v_mul_f32_e32 v6, v0, v5
	v_exp_f32_e32 v2, v2
	v_fma_f32 v7, -v4, v6, v0
	v_fmac_f32_e32 v6, v7, v5
	v_fma_f32 v0, -v4, v6, v0
	v_div_fmas_f32 v0, v0, v5, v6
	v_add_f32_e32 v2, 1.0, v2
	v_div_fixup_f32 v0, v0, v3, v37
	v_div_scale_f32 v3, s[12:13], v2, v2, v28
	v_rcp_f32_e32 v4, v3
	v_bfe_u32 v5, v0, 16, 1
	v_add3_u32 v0, v0, v5, s14
	global_store_short_d16_hi v[10:11], v0, off offset:768
	v_fma_f32 v0, -v3, v4, 1.0
	v_fmac_f32_e32 v4, v0, v4
	v_div_scale_f32 v0, vcc, v28, v2, v28
	v_mul_f32_e32 v5, v0, v4
	v_fma_f32 v6, -v3, v5, v0
	v_fmac_f32_e32 v5, v6, v4
	v_fma_f32 v0, -v3, v5, v0
	v_div_fmas_f32 v0, v0, v4, v5
	v_div_fixup_f32 v0, v0, v2, v28
	v_bfe_u32 v2, v0, 16, 1
	v_add3_u32 v0, v0, v2, s14
	s_and_b64 vcc, exec, s[38:39]
	global_store_short_d16_hi v[10:11], v0, off offset:896
	s_barrier
	s_cbranch_vccnz .LBB0_451

; __device__ __forceinline__ int obid() { int b = (int)blockIdx.x; asm volatile("" : "+s"(b)); return b; }
; __device__ __forceinline__ void ph_final(const Params& p_) {
;     ...
;     for (int row = obid() * 8 + wave; row < MTOK; row += 2 * stride) {
;         const bool two = (row + stride < MTOK);
;         f32x4* xr0 = (f32x4*)(p.out + (size_t)row * DM) + lane; f32x4* xr1 = (f32x4*)(p.out + (size_t)(two ? row + stride : row) * DM) + lane;
;         f32x4 v0[8], v1[8], g4[8];
; #pragma unroll
;         for (int j = 0; j < 8; ++j) { v0[j] = xr0[64 * j]; v1[j] = xr1[64 * j]; g4[j] = *(const f32x4*)(p.final_g + (64 * j + lane) * 4); }
;         asm volatile("" ::: "memory");
;         float s0 = 0.f, s1 = 0.f;
; #pragma unroll
;         for (int j = 0; j < 8; ++j) { s0 += (v0[j][0] * v0[j][0] + v0[j][1] * v0[j][1]) + (v0[j][2] * v0[j][2] + v0[j][3] * v0[j][3]); s1 += (v1[j][0] * v1[j][0] + v1[j][1] * v1[j][1]) + (v1[j][2] * v1[j][2] + v1[j][3] * v1[j][3]); }
.LBB0_823:
	v_ashrrev_i32_e32 v1, 31, v0
	v_lshlrev_b64 v[2:3], 13, v[0:1]
	v_lshl_add_u64 v[112:113], v[96:97], 0, v[2:3]
	v_add_co_u32_e32 v4, vcc, s17, v112
	v_add_u32_e32 v124, s94, v0
	s_nop 0
	v_addc_co_u32_e32 v5, vcc, 0, v113, vcc
	v_cmp_gt_i32_e32 vcc, s15, v124
	global_load_dwordx4 v[92:95], v[112:113], off
	global_load_dwordx4 v[72:75], v[112:113], off offset:1024
	global_load_dwordx4 v[68:71], v[112:113], off offset:2048
	global_load_dwordx4 v[48:51], v[112:113], off offset:3072
	v_cndmask_b32_e32 v0, v0, v124, vcc
	v_ashrrev_i32_e32 v1, 31, v0
	v_lshlrev_b64 v[0:1], 13, v[0:1]
	v_lshl_add_u64 v[110:111], v[96:97], 0, v[0:1]
	global_load_dwordx4 v[44:47], v[4:5], off
	global_load_dwordx4 v[84:87], v[110:111], off
	global_load_dwordx4 v[80:83], v[110:111], off offset:1024
	global_load_dwordx4 v[60:63], v[110:111], off offset:2048
	v_add_co_u32_e32 v6, vcc, s17, v110
	s_waitcnt vmcnt(0)
	v_mov_b32_e32 v116, v93
	v_addc_co_u32_e32 v7, vcc, 0, v111, vcc
	global_load_dwordx4 v[36:39], v[6:7], off
	global_load_dwordx4 v[56:59], v[110:111], off offset:3072
	global_load_dwordx4 v[88:91], v[98:99], off
	global_load_dwordx4 v[76:79], v[98:99], off offset:1024
	global_load_dwordx4 v[64:67], v[98:99], off offset:2048
	global_load_dwordx4 v[52:55], v[98:99], off offset:3072
	global_load_dwordx4 v[28:31], v[4:5], off offset:1024
	global_load_dwordx4 v[40:43], v[100:101], off
	global_load_dwordx4 v[24:27], v[102:103], off
	global_load_dwordx4 v[12:15], v[104:105], off
	global_load_dwordx4 v[0:3], v[106:107], off
	global_load_dwordx4 v[32:35], v[6:7], off offset:1024
	global_load_dwordx4 v[20:23], v[4:5], off offset:2048
	global_load_dwordx4 v[8:11], v[4:5], off offset:3072
	global_load_dwordx4 v[16:19], v[6:7], off offset:2048
	s_nop 0
	global_load_dwordx4 v[4:7], v[6:7], off offset:3072
	v_mov_b32_e32 v117, v73
	v_mov_b32_e32 v128, v95
	v_mov_b32_e32 v129, v75
	v_mov_b32_e32 v114, v92
	v_mov_b32_e32 v115, v72
	v_mov_b32_e32 v126, v94
	v_mov_b32_e32 v127, v74
	v_pk_mul_f32 v[116:117], v[116:117], v[116:117]
	v_pk_mul_f32 v[128:129], v[128:129], v[128:129]
	v_pk_mul_f32 v[130:131], v[70:71], v[70:71]
	v_pk_mul_f32 v[132:133], v[68:69], v[68:69]
	v_mul_f32_e32 v134, v49, v49
	v_pk_fma_f32 v[114:115], v[114:115], v[114:115], v[116:117]
	v_pk_fma_f32 v[116:117], v[126:127], v[126:127], v[128:129]
	v_mov_b32_e32 v128, v85
	v_mov_b32_e32 v129, v81
	v_mov_b32_e32 v140, v87
	v_mov_b32_e32 v141, v83
	v_pk_mov_b32 v[138:139], v[132:133], v[130:131] op_sel:[1,0]
	v_mov_b32_e32 v133, v131
	v_pk_fma_f32 v[130:131], v[48:49], v[48:49], v[134:135] op_sel_hi:[1,1,0]
	v_mov_b32_e32 v126, v84
	v_mov_b32_e32 v127, v80
	v_mov_b32_e32 v134, v86
	v_mov_b32_e32 v135, v82
	v_pk_add_f32 v[114:115], v[114:115], v[116:117]
	v_pk_mul_f32 v[116:117], v[128:129], v[128:129]
	v_pk_mul_f32 v[128:129], v[140:141], v[140:141]
	v_mul_f32_e32 v136, v51, v51
	v_mul_f32_e32 v137, v45, v45
	v_pk_add_f32 v[132:133], v[138:139], v[132:133]
	v_pk_fma_f32 v[116:117], v[126:127], v[126:127], v[116:117]
	v_pk_fma_f32 v[126:127], v[134:135], v[134:135], v[128:129]
	v_mul_f32_e32 v125, v44, v44
	v_mul_f32_e32 v144, v46, v46
	v_mul_f32_e32 v145, v47, v47
	v_pk_mul_f32 v[138:139], v[62:63], v[62:63]
	v_pk_mul_f32 v[142:143], v[60:61], v[60:61]
	v_pk_add_f32 v[132:133], v[132:133], v[132:133] op_sel:[0,1] op_sel_hi:[1,0]
	v_pk_add_f32 v[114:115], v[114:115], v[114:115] op_sel:[0,1] op_sel_hi:[1,0]
	v_pk_add_f32 v[116:117], v[116:117], v[126:127]
	v_pk_fma_f32 v[126:127], v[50:51], v[50:51], v[136:137] op_sel_hi:[1,1,0]
	v_mov_b32_e32 v131, v144
	v_pk_mov_b32 v[140:141], v[142:143], v[138:139] op_sel:[1,0]
	v_mov_b32_e32 v143, v139
	v_mov_b32_e32 v133, v137
	v_mov_b32_e32 v115, v125
	v_mov_b32_e32 v127, v145
	v_pk_add_f32 v[128:129], v[140:141], v[142:143]
	v_pk_add_f32 v[114:115], v[114:115], v[132:133]
	v_pk_add_f32 v[126:127], v[130:131], v[126:127]
	v_pk_add_f32 v[116:117], v[116:117], v[116:117] op_sel:[0,1] op_sel_hi:[1,0]
	v_pk_add_f32 v[114:115], v[114:115], v[126:127]
	v_pk_add_f32 v[126:127], v[128:129], v[128:129] op_sel:[0,1] op_sel_hi:[1,0]
	v_pk_add_f32 v[114:115], v[114:115], v[114:115] op_sel:[0,1] op_sel_hi:[1,0]
	v_cmp_lt_i32_e32 vcc, v118, v109
	s_waitcnt vmcnt(15)
	v_mul_f32_e32 v125, v36, v36
	v_mul_f32_e32 v130, v37, v37
	v_mov_b32_e32 v117, v125
	v_mov_b32_e32 v127, v130
	v_pk_add_f32 v[116:117], v[116:117], v[126:127]
	s_waitcnt vmcnt(14)
	v_mul_f32_e32 v126, v57, v57
	v_mul_f32_e32 v128, v59, v59
	v_mul_f32_e32 v131, v38, v38
	v_mul_f32_e32 v132, v39, v39
	v_pk_fma_f32 v[126:127], v[56:57], v[56:57], v[126:127] op_sel_hi:[1,1,0]
	v_pk_fma_f32 v[128:129], v[58:59], v[58:59], v[128:129] op_sel_hi:[1,1,0]
	v_mov_b32_e32 v127, v131
	v_mov_b32_e32 v129, v132
	v_pk_add_f32 v[126:127], v[126:127], v[128:129]
	s_waitcnt vmcnt(9)
	v_pk_mul_f32 v[128:129], v[28:29], v[28:29]
	v_pk_add_f32 v[116:117], v[116:117], v[126:127]
	v_pk_mul_f32 v[126:127], v[30:31], v[30:31]
	s_waitcnt vmcnt(2)
; __device__ __forceinline__ void ph_final(const Params& p_) {
;     ...
;         for (int j = 0; j < 8; ++j) { s0 += (v0[j][0] * v0[j][0] + v0[j][1] * v0[j][1]) + (v0[j][2] * v0[j][2] + v0[j][3] * v0[j][3]); s1 += (v1[j][0] * v1[j][0] + v1[j][1] * v1[j][1]) + (v1[j][2] * v1[j][2] + v1[j][3] * v1[j][3]); }
;         s0 = wave_sum(s0); s1 = wave_sum(s1);
;         const float r0 = rsqrtf(s0 * (1.f / DM) + 1e-6f), r1 = rsqrtf(s1 * (1.f / DM) + 1e-6f);
; #pragma unroll
;         for (int j = 0; j < 8; ++j) { xr0[64 * j] = v0[j] * r0 * g4[j]; if (two) xr1[64 * j] = v1[j] * r1 * g4[j]; }
	v_mul_f32_e32 v125, v8, v8
	v_pk_mov_b32 v[130:131], v[128:129], v[126:127] op_sel:[1,0]
	v_mov_b32_e32 v129, v127
	v_pk_add_f32 v[126:127], v[130:131], v[128:129]
	v_pk_mul_f32 v[128:129], v[34:35], v[34:35]
	v_pk_mul_f32 v[130:131], v[32:33], v[32:33]
	v_pk_add_f32 v[126:127], v[126:127], v[126:127] op_sel:[0,1] op_sel_hi:[1,0]
	v_pk_mov_b32 v[132:133], v[130:131], v[128:129] op_sel:[1,0]
	v_mov_b32_e32 v131, v129
	v_pk_add_f32 v[128:129], v[132:133], v[130:131]
	v_mul_f32_e32 v130, v9, v9
	v_mov_b32_e32 v115, v125
	v_mov_b32_e32 v127, v130
	v_pk_add_f32 v[114:115], v[114:115], v[126:127]
	v_mul_f32_e32 v126, v21, v21
	v_mul_f32_e32 v131, v10, v10
	v_pk_fma_f32 v[126:127], v[20:21], v[20:21], v[126:127] op_sel_hi:[1,1,0]
	v_mul_f32_e32 v130, v23, v23
	v_mul_f32_e32 v132, v11, v11
	v_mov_b32_e32 v127, v131
	v_pk_fma_f32 v[130:131], v[22:23], v[22:23], v[130:131] op_sel_hi:[1,1,0]
	s_waitcnt vmcnt(0)
	v_mul_f32_e32 v125, v4, v4
	v_mov_b32_e32 v131, v132
	v_pk_add_f32 v[126:127], v[126:127], v[130:131]
	v_mul_f32_e32 v130, v5, v5
	v_pk_add_f32 v[114:115], v[114:115], v[126:127]
	v_pk_add_f32 v[116:117], v[116:117], v[116:117] op_sel:[0,1] op_sel_hi:[1,0]
	v_pk_add_f32 v[126:127], v[128:129], v[128:129] op_sel:[0,1] op_sel_hi:[1,0]
	v_mov_b32_e32 v117, v125
	v_mov_b32_e32 v127, v130
	v_pk_add_f32 v[116:117], v[116:117], v[126:127]
	v_mul_f32_e32 v126, v17, v17
	v_mul_f32_e32 v128, v19, v19
	v_mul_f32_e32 v131, v6, v6
	v_mul_f32_e32 v132, v7, v7
	v_pk_fma_f32 v[126:127], v[16:17], v[16:17], v[126:127] op_sel_hi:[1,1,0]
	v_pk_fma_f32 v[128:129], v[18:19], v[18:19], v[128:129] op_sel_hi:[1,1,0]
	v_mov_b32_e32 v127, v131
	v_mov_b32_e32 v129, v132
	v_pk_add_f32 v[126:127], v[126:127], v[128:129]
	v_cndmask_b32_e32 v125, v178, v118, vcc
	v_pk_add_f32 v[116:117], v[116:117], v[126:127]
	v_mov_b32_e32 v127, v114
	v_mov_b32_e32 v126, v116
	v_mov_b32_e32 v114, v117
	v_lshlrev_b32_e32 v125, 2, v125
	v_pk_add_f32 v[114:115], v[126:127], v[114:115]
	s_nop 1
	v_mov_b32_dpp v117, v115 quad_perm:[1,0,3,2] row_mask:0xf bank_mask:0xf
	v_mov_b32_dpp v116, v114 quad_perm:[1,0,3,2] row_mask:0xf bank_mask:0xf
	v_cmp_lt_i32_e32 vcc, v119, v109
	s_waitcnt lgkmcnt(0)
	v_pk_add_f32 v[114:115], v[114:115], v[116:117]
	v_cndmask_b32_e32 v125, v178, v119, vcc
	v_lshlrev_b32_e32 v125, 2, v125
	s_nop 1
	v_mov_b32_dpp v117, v115 quad_perm:[2,3,0,1] row_mask:0xf bank_mask:0xf
	v_mov_b32_dpp v116, v114 quad_perm:[2,3,0,1] row_mask:0xf bank_mask:0xf
	v_cmp_lt_i32_e32 vcc, v120, v109
	s_waitcnt lgkmcnt(0)
	v_pk_add_f32 v[114:115], v[114:115], v[116:117]
	v_cndmask_b32_e32 v125, v178, v120, vcc
	v_lshlrev_b32_e32 v125, 2, v125
	s_nop 1
	v_mov_b32_dpp v117, v115 row_half_mirror row_mask:0xf bank_mask:0xf
	v_mov_b32_dpp v116, v114 row_half_mirror row_mask:0xf bank_mask:0xf
	v_cmp_lt_i32_e32 vcc, v121, v109
	s_waitcnt lgkmcnt(0)
	v_pk_add_f32 v[114:115], v[114:115], v[116:117]
	v_cndmask_b32_e32 v125, v178, v121, vcc
	v_lshlrev_b32_e32 v125, 2, v125
	s_nop 1
	v_mov_b32_dpp v117, v115 row_mirror row_mask:0xf bank_mask:0xf
	v_mov_b32_dpp v116, v114 row_mirror row_mask:0xf bank_mask:0xf
	v_cmp_lt_i32_e32 vcc, v122, v109
	s_waitcnt lgkmcnt(0)
	v_pk_add_f32 v[114:115], v[114:115], v[116:117]
	v_cndmask_b32_e32 v125, v178, v122, vcc
	v_lshlrev_b32_e32 v125, 2, v125
	v_mov_b32_e32 v117, v115
	v_mov_b32_e32 v116, v114
	s_nop 1
	v_permlane16_swap_b32_e32 v115, v117
	v_permlane16_swap_b32_e32 v114, v116
	v_cmp_lt_i32_e32 vcc, v123, v109
	s_waitcnt lgkmcnt(0)
	v_pk_add_f32 v[114:115], v[114:115], v[116:117]
	v_cndmask_b32_e32 v125, v178, v123, vcc
	v_lshlrev_b32_e32 v125, 2, v125
	v_mov_b32_e32 v117, v115
	v_mov_b32_e32 v116, v114
	s_nop 1
	v_permlane32_swap_b32_e32 v115, v117
	v_permlane32_swap_b32_e32 v114, v116
	v_cmp_lt_i32_e32 vcc, s16, v124
	s_waitcnt lgkmcnt(0)
	v_pk_add_f32 v[114:115], v[114:115], v[116:117]
	s_nop 0
	v_pk_fma_f32 v[116:117], v[114:115], s[14:15], v[108:109] op_sel_hi:[1,0,0]
	s_nop 0
	v_mul_f32_e32 v114, 0x4b800000, v117
	v_cmp_gt_f32_e64 s[2:3], s18, v117
	v_cmp_gt_f32_e64 s[0:1], s18, v116
	s_nop 0
	v_cndmask_b32_e64 v114, v117, v114, s[2:3]
	v_rsq_f32_e32 v114, v114
	s_nop 0
	v_mul_f32_e32 v115, 0x45800000, v114
	v_cndmask_b32_e64 v114, v114, v115, s[2:3]
	v_mov_b32_e32 v115, v114
	v_pk_mul_f32 v[92:93], v[92:93], v[114:115] op_sel_hi:[1,0]
	v_pk_mul_f32 v[94:95], v[94:95], v[114:115] op_sel_hi:[1,0]
	v_pk_mul_f32 v[92:93], v[88:89], v[92:93]
	v_pk_mul_f32 v[94:95], v[90:91], v[94:95]
	global_store_dwordx4 v[112:113], v[92:95], off
	s_nop 1
	v_pk_mul_f32 v[92:93], v[72:73], v[114:115]
	s_and_saveexec_b64 s[2:3], vcc
	s_xor_b64 s[2:3], exec, s[2:3]
	s_cbranch_execz .LBB0_825
	v_mov_b32_e32 v72, v114
	v_mov_b32_e32 v73, v114
	v_pk_mul_f32 v[72:73], v[74:75], v[72:73]
	s_nop 0
	v_pk_mul_f32 v[74:75], v[78:79], v[72:73]
	v_pk_mul_f32 v[72:73], v[76:77], v[92:93]
	global_store_dwordx4 v[112:113], v[72:75], off offset:1024
